# P3: u rows of two experts fetched by one global_load_lds_dwordx4 into a wave-private LDS slot and read back with ds_read_b64
# speedup vs baseline: 1.0008x; 1.0008x over previous
; __device__ __forceinline__ float bf_lo(unsigned u) { return __uint_as_float(u << 16); }
; __device__ __forceinline__ float bf_hi(unsigned u) { return __uint_as_float(u & 0xffff0000u); }
; __device__ __forceinline__ int vblk() { return (int)blockIdx.x * 2 + half_id(); }
; __device__ __forceinline__ int vgrid() { return (int)gridDim.x * 2; }
; __device__ __forceinline__ void p3_token(const Params& p, int tok, int lane, unsigned* rec, float& sh, int& hs8) {
;     const bf16_t* H = (const bf16_t*)(p.ws + OFF_H);
;     const int* eidx = (const int*)(p.ws + OFF_EIDX);
;     const float* gwp = (const float*)(p.ws + OFF_GW);
;     {
;         const u32x4 a = *(const u32x4*)(H + (size_t)tok * DM + lane * 16), b = *(const u32x4*)(H + (size_t)tok * DM + lane * 16 + 8);
;         const unsigned hw[8] = {a.x, a.y, a.z, a.w, b.x, b.y, b.z, b.w};
;         float hv[16];
;         float mx = 0.f;
; #pragma unroll
;         for (int i = 0; i < 8; i++) { hv[2 * i] = bf_lo(hw[i]); hv[2 * i + 1] = bf_hi(hw[i]); mx = fmaxf(mx, fmaxf(fabsf(hv[2 * i]), fabsf(hv[2 * i + 1]))); }
;         mx = wave_max(mx);
; __device__ void phaseP3(const Params& p, float* dstp, char* lds) {
;     const int tid_ = TIDX; const int lane = tid_ & 63, wave = tid_ >> 6;
;     const unsigned char* UQ = (const unsigned char*)(p.ws + OFF_UB);
;     const unsigned char* VQ = UQ + 16777216;
;     const float* tsc = (const float*)(p.ws + OFF_UB + 33554432);
;     const int ul = ((lane & 1) << 1) | ((lane >> 1) & 1);
;     constexpr int TPW = 2;
;     unsigned* recs = (unsigned*)(lds + wave * TPW * P3_REC);
;     for (int tb = (vblk() * 4 + wave) * TPW; tb < NTOK; tb += vgrid() * 4 * TPW) {
.LBB0_1040:
	s_or_b64 exec, exec, s[4:5]
	v_readfirstlane_b32 s0, v158
	v_readlane_b32 s1, v222, 0
	s_lshr_b32 s0, s0, 5
	v_mov_b32_e32 v1, v158
	s_lshl_b32 s1, s1, 4
	s_and_b32 s0, s0, 0x7fffff8
	s_waitcnt lgkmcnt(0)
	s_barrier
	s_add_i32 s0, s0, s1
	v_bfe_u32 v0, v1, 6, 2
	v_lshl_or_b32 v8, v0, 1, s0
	s_movk_i32 s0, 0x4000
	v_cmp_gt_i32_e32 vcc, s0, v8
	s_and_saveexec_b64 s[0:1], vcc
	s_cbranch_execz .LBB0_1077
	s_movk_i32 s8, 0x1400
	v_mov_b32_e32 v2, s33
	v_mad_u32_u24 v11, v0, s8, v2
	v_and_b32_e32 v2, 64, v159
	v_add_u32_e32 v2, 64, v2
	v_xor_b32_e32 v3, 32, v159
	v_cmp_lt_i32_e32 vcc, v3, v2
	s_load_dwordx4 s[20:23], s[80:81], 0xd0
	s_load_dwordx2 s[4:5], s[80:81], 0x38
	v_cndmask_b32_e32 v3, v159, v3, vcc
	v_lshlrev_b32_e32 v112, 2, v3
	v_xor_b32_e32 v3, 16, v159
	v_cmp_lt_i32_e32 vcc, v3, v2
	v_and_b32_e32 v10, 63, v1
	v_mov_b32_e32 v13, 0
	v_cndmask_b32_e32 v3, v159, v3, vcc
	v_lshlrev_b32_e32 v113, 2, v3
	v_xor_b32_e32 v3, 8, v159
	v_cmp_lt_i32_e32 vcc, v3, v2
	v_lshlrev_b32_e32 v12, 4, v10
	s_mov_b64 s[0:1], 0x9c00000
	v_cndmask_b32_e32 v3, v159, v3, vcc
	v_lshlrev_b32_e32 v114, 2, v3
	v_xor_b32_e32 v3, 4, v159
	v_cmp_lt_i32_e32 vcc, v3, v2
	s_lshl_b32 s36, s72, 4
	v_bfrev_b32_e32 v4, v1
	v_cndmask_b32_e32 v3, v159, v3, vcc
	v_lshlrev_b32_e32 v115, 2, v3
	v_xor_b32_e32 v3, 2, v159
	v_cmp_lt_i32_e32 vcc, v3, v2
	s_waitcnt vmcnt(3) lgkmcnt(0)
	v_lshl_add_u64 v[18:19], s[20:21], 0, v[12:13]
	s_add_u32 s20, s22, 0xdd00000
	v_cndmask_b32_e32 v3, v159, v3, vcc
	v_lshlrev_b32_e32 v116, 2, v3
	v_xor_b32_e32 v3, 1, v159
	v_cmp_lt_i32_e32 vcc, v3, v2
	s_addc_u32 s21, s23, 0
	v_mov_b32_e32 v5, v13
	v_cndmask_b32_e32 v2, v159, v3, vcc
	v_lshlrev_b32_e32 v117, 2, v2
	v_lshlrev_b32_e32 v2, 3, v10
	v_mov_b32_e32 v3, v13
	v_lshl_add_u64 v[2:3], s[22:23], 0, v[2:3]
	v_lshl_add_u64 v[14:15], v[2:3], 0, s[0:1]
	s_mov_b64 s[0:1], 0xac00000
	v_lshl_add_u64 v[16:17], v[2:3], 0, s[0:1]
	v_and_b32_e32 v2, 1, v1
	v_lshrrev_b32_e32 v3, 28, v4
	v_cmp_eq_u32_e64 s[0:1], 0, v2
	v_lshlrev_b32_e32 v2, 6, v10
	v_and_b32_e32 v6, 12, v3
	v_lshlrev_b32_e32 v4, 5, v10
	s_add_u32 s24, s22, 0xe500000
	v_mov_b32_e32 v3, v13
	v_and_b32_e32 v1, 2, v1
	v_add_u32_e32 v118, v11, v2
	v_lshl_add_u64 v[4:5], s[22:23], 0, v[4:5]
	s_mov_b64 s[6:7], 0x1c00000
	s_addc_u32 s25, s23, 0
	s_waitcnt vmcnt(1)
	v_lshl_add_u64 v[24:25], s[4:5], 0, v[2:3]
	v_mov_b32_e32 v2, s33
	v_cmp_eq_u32_e64 s[2:3], 0, v1
	v_mul_i32_i24_e32 v1, 0xffffffd0, v10
	v_lshl_add_u64 v[20:21], v[4:5], 0, s[6:7]
	s_add_u32 s26, s22, 0xbc00000
	s_mov_b64 s[6:7], 0xbd00000
	v_mad_u32_u24 v0, v0, s8, v2
	s_movk_i32 s4, 0x210
	v_add_u32_e32 v119, v11, v6
	s_addc_u32 s27, s23, 0
	v_lshl_add_u64 v[22:23], v[4:5], 0, s[6:7]
	v_add3_u32 v120, v0, v6, s4
	v_add_u32_e32 v121, 16, v0
	s_mov_b64 s[28:29], 0
	s_mov_b32 s33, 0x42ee0000
	v_mov_b32_e32 v122, 0x80
	s_movk_i32 s37, 0x800
	v_mov_b32_e32 v123, 0x800
	v_mov_b32_e32 v124, 0x8000
	v_mov_b32_e32 v125, 0x80000
	s_mov_b32 s38, 0x800000
	v_mov_b32_e32 v126, 0x800000
	v_bfrev_b32_e32 v127, 16
	v_add_u32_e32 v128, v118, v1
	s_mov_b32 s39, 0x3e6d3388
	v_mov_b32_e32 v129, 0xbf3a00e3
	v_lshlrev_b32_e32 v26, 2, v12
	s_mov_b64 s[30:31], 0x9000
	s_mov_b32 s40, 0x9000
	v_mov_b32_e32 v130, 0x358637bd
	s_movk_i32 s41, 0x3fff
	s_add_u32 s50, s22, 0x9c00000
	s_addc_u32 s51, s23, 0
	s_add_u32 s52, s22, 0xac00000
	s_addc_u32 s53, s23, 0
	v_lshlrev_b32_e32 v136, 3, v159
	v_and_b32_e32 v138, 16, v159
	v_mov_b32_e32 v137, 0xa00
	v_cmp_ne_u32_e64 s[54:55], 0, v138
	s_nop 1
	v_cndmask_b32_e64 v137, 0, v137, s[54:55]
	v_add_u32_e32 v137, v120, v137
	v_readfirstlane_b32 s56, v158
	s_lshr_b32 s57, s56, 8
	s_mul_i32 s57, s57, 0x12000
	s_lshr_b32 s56, s56, 6
	s_and_b32 s56, s56, 3
	s_lshl_b32 s56, s56, 12
	s_add_i32 s56, s56, s57
	s_add_i32 s56, s56, 0x8000
	v_and_b32_e32 v148, 31, v159
	v_lshlrev_b32_e32 v148, 4, v148
	v_lshl_add_u32 v149, v159, 3, s56
	s_mov_b32 s58, -1
	s_mov_b32 s59, 0
.LBB0_1042:
	v_ashrrev_i32_e32 v9, 31, v8
	s_waitcnt vmcnt(0)
	v_lshlrev_b64 v[28:29], 11, v[8:9]
	v_lshl_add_u64 v[30:31], v[20:21], 0, v[28:29]
	global_load_dwordx4 v[0:3], v[30:31], off
	global_load_dwordx4 v[4:7], v[30:31], off offset:16
	s_waitcnt vmcnt(1)
	v_lshlrev_b32_e32 v12, 16, v0
	v_and_b32_e32 v27, 0xffff0000, v0
	v_lshlrev_b32_e32 v36, 16, v1
	v_and_b32_e32 v37, 0xffff0000, v1
	v_lshlrev_b32_e32 v38, 16, v2
	v_and_b32_e32 v39, 0xffff0000, v2
	v_lshlrev_b32_e32 v40, 16, v3
	v_and_b32_e32 v41, 0xffff0000, v3
	v_max_f32_e64 v0, |v27|, |v27|
	v_max_f32_e64 v1, |v12|, |v12|
	v_max_f32_e64 v2, |v37|, |v37|
	v_max_f32_e64 v3, |v36|, |v36|
	s_waitcnt vmcnt(0)
	v_lshlrev_b32_e32 v42, 16, v4
	v_and_b32_e32 v43, 0xffff0000, v4
	v_lshlrev_b32_e32 v44, 16, v5
	v_and_b32_e32 v5, 0xffff0000, v5
	v_lshlrev_b32_e32 v45, 16, v6
	v_and_b32_e32 v46, 0xffff0000, v6
	v_lshlrev_b32_e32 v47, 16, v7
	v_and_b32_e32 v48, 0xffff0000, v7
	v_max_f32_e64 v4, |v39|, |v39|
	v_max_f32_e64 v6, |v38|, |v38|
	v_max_f32_e64 v7, |v41|, |v41|
	v_max_f32_e64 v30, |v40|, |v40|
	v_max_f32_e32 v0, v1, v0
	v_max_f32_e32 v1, v3, v2
	v_max_f32_e64 v31, |v43|, |v43|
	v_max_f32_e64 v32, |v42|, |v42|
	v_max_f32_e64 v33, |v5|, |v5|
	v_max_f32_e64 v34, |v44|, |v44|
	v_max_f32_e32 v2, v6, v4
	v_max_f32_e32 v3, v30, v7
	v_max3_f32 v0, v0, 0, v1
	v_max_f32_e64 v35, |v46|, |v46|
	v_max_f32_e64 v49, |v45|, |v45|
	v_max_f32_e64 v50, |v48|, |v48|
	v_max_f32_e64 v51, |v47|, |v47|
	v_max_f32_e32 v4, v32, v31
	v_max_f32_e32 v6, v34, v33
	v_max3_f32 v0, v0, v2, v3
	v_max_f32_e32 v7, v49, v35
	v_max_f32_e32 v30, v51, v50
	v_max3_f32 v0, v0, v4, v6
	v_max3_f32 v0, v0, v7, v30
	ds_bpermute_b32 v1, v112, v0
	s_waitcnt lgkmcnt(0)
; __device__ __forceinline__ void p3_token(const Params& p, int tok, int lane, unsigned* rec, float& sh, int& hs8) {
;     ...
;         mx = wave_max(mx);
;         const float inv = mx > 0.f ? 119.f / mx : 0.f;
;         sh = mx * (1.f / 119.f);
;         unsigned qh[4] = {0u, 0u, 0u, 0u};
; #pragma unroll
;         for (int e = 0; e < 16; e++) {
;             const int qi = (int)rintf(hv[e] * inv);
;             const int hh = (qi + 8) >> 4, hl = qi - 16 * hh;
;             qh[(e >> 3) * 2] |= (unsigned)(hh & 15) << ((e & 7) * 4);
;             qh[(e >> 3) * 2 + 1] |= (unsigned)(hl & 15) << ((e & 7) * 4);
;         }
;         hs8 = 0;
;         *(u32x4*)(rec + 256 + lane * 4) = (u32x4){qh[0], qh[1], qh[2], qh[3]};
;     }
;     const int e0 = eidx[(size_t)tok * 128 + lane], e1 = eidx[(size_t)tok * 128 + 64 + lane];
;     const float g0 = gwp[(size_t)tok * 128 + lane], g1 = gwp[(size_t)tok * 128 + 64 + lane];
;     const int k0 = e0 >> 11, k1 = e1 >> 11;
;     int pos0 = 0, pos1 = 0, base = 0;
; #pragma unroll
;     for (int v = 0; v < 8; v++) {
;         const unsigned long long m0 = __ballot(k0 == v), m1 = __ballot(k1 == v);
;         const int c0 = __popcll(m0);
;         const int r0 = __builtin_amdgcn_mbcnt_hi((unsigned)(m0 >> 32), __builtin_amdgcn_mbcnt_lo((unsigned)m0, 0u));
;         const int r1 = __builtin_amdgcn_mbcnt_hi((unsigned)(m1 >> 32), __builtin_amdgcn_mbcnt_lo((unsigned)m1, 0u));
;         pos0 = (k0 == v) ? base + r0 : pos0;
;         pos1 = (k1 == v) ? base + c0 + r1 : pos1;
;         base += c0 + __popcll(m1);
;     }
	v_max_f32_e32 v1, v1, v1
	v_max_f32_e32 v0, v0, v1
	ds_bpermute_b32 v1, v113, v0
	s_waitcnt lgkmcnt(0)
	v_max_f32_e32 v1, v1, v1
	v_max_f32_e32 v0, v0, v1
	ds_bpermute_b32 v1, v114, v0
	s_waitcnt lgkmcnt(0)
	v_max_f32_e32 v1, v1, v1
	v_max_f32_e32 v0, v0, v1
	ds_bpermute_b32 v1, v115, v0
	s_waitcnt lgkmcnt(0)
	v_max_f32_e32 v1, v1, v1
	v_max_f32_e32 v2, v0, v1
	ds_bpermute_b32 v4, v116, v2
	v_lshlrev_b64 v[0:1], 9, v[8:9]
	v_lshl_or_b32 v0, v10, 2, v0
	v_mov_b32_e32 v3, v1
	v_lshl_add_u64 v[6:7], s[20:21], 0, v[0:1]
	s_waitcnt lgkmcnt(0)
	v_max_f32_e32 v4, v4, v4
	v_max_f32_e32 v4, v2, v4
	ds_bpermute_b32 v49, v117, v4
	v_or_b32_e32 v2, 0x100, v0
	v_lshl_add_u64 v[30:31], s[24:25], 0, v[0:1]
	v_lshl_add_u64 v[32:33], s[20:21], 0, v[2:3]
	v_lshl_add_u64 v[34:35], s[24:25], 0, v[2:3]
	s_waitcnt lgkmcnt(0)
	v_max_f32_e32 v0, v49, v49
	v_max_f32_e32 v0, v4, v0
	global_load_dword v4, v[6:7], off
	global_load_dword v1, v[32:33], off
	global_load_dword v2, v[30:31], off
	global_load_dword v3, v[34:35], off
	v_div_scale_f32 v49, s[4:5], v0, v0, s33
	v_rcp_f32_e32 v50, v49
	v_div_scale_f32 v6, vcc, s33, v0, s33
	v_fma_f32 v7, -v49, v50, 1.0
	v_fmac_f32_e32 v50, v7, v50
	v_mul_f32_e32 v7, v6, v50
	v_fma_f32 v30, -v49, v7, v6
	v_fmac_f32_e32 v7, v30, v50
	v_fma_f32 v6, -v49, v7, v6
	v_div_fmas_f32 v6, v6, v50, v7
	v_div_fixup_f32 v6, v6, v0, s33
	v_cmp_lt_f32_e32 vcc, 0, v0
	s_waitcnt vmcnt(2)
	v_cmp_gt_u32_e64 s[4:5], s37, v1
	v_cndmask_b32_e32 v6, 0, v6, vcc
	v_mul_f32_e32 v7, v6, v12
	v_mul_f32_e32 v12, v6, v27
	v_mul_f32_e32 v27, v6, v36
	v_mul_f32_e32 v30, v6, v37
	v_rndne_f32_e32 v7, v7
	v_rndne_f32_e32 v12, v12
	v_mul_f32_e32 v31, v6, v38
	v_mul_f32_e32 v32, v6, v39
	v_mul_f32_e32 v34, v6, v41
	v_rndne_f32_e32 v27, v27
	v_rndne_f32_e32 v30, v30
	v_cvt_i32_f32_e32 v7, v7
	v_cvt_i32_f32_e32 v12, v12
	v_mul_f32_e32 v33, v6, v40
	v_rndne_f32_e32 v31, v31
	v_rndne_f32_e32 v32, v32
	v_rndne_f32_e32 v34, v34
	v_cvt_i32_f32_e32 v27, v27
	v_cvt_i32_f32_e32 v30, v30
	v_rndne_f32_e32 v33, v33
	v_cvt_i32_f32_e32 v31, v31
	v_cvt_i32_f32_e32 v32, v32
	v_cvt_i32_f32_e32 v34, v34
	v_cvt_i32_f32_e32 v33, v33
	v_add_u32_e32 v36, 8, v7
	v_add_u32_e32 v37, 8, v12
	v_and_b32_e32 v7, 15, v7
	v_lshlrev_b32_e32 v12, 4, v12
	v_lshl_add_u32 v38, v27, 4, v122
	v_lshlrev_b32_e32 v27, 8, v27
	v_lshl_add_u32 v39, v30, 8, v123
	v_lshrrev_b32_e32 v36, 4, v36
	v_and_b32_e32 v37, 0xf0, v37
	v_lshl_add_u32 v40, v31, 12, v124
	v_lshl_add_u32 v41, v32, 16, v125
	v_lshl_add_u32 v49, v34, 24, v127
	v_and_b32_e32 v12, 0xf0, v12
	v_and_b32_e32 v38, 0xf00, v38
	v_and_b32_e32 v27, 0xf00, v27
	v_and_b32_e32 v39, 0xf000, v39
	v_lshl_or_b32 v7, v34, 28, v7
	v_and_or_b32 v34, v36, 15, v37
	v_mul_f32_e32 v35, v6, v42
	v_lshlrev_b32_e32 v30, 12, v30
	v_lshlrev_b32_e32 v31, 16, v31
	v_lshl_add_u32 v42, v33, 20, v126
	v_and_b32_e32 v40, 0xf0000, v40
	v_and_b32_e32 v41, 0xf00000, v41
	v_or3_b32 v7, v7, v12, v27
	v_or3_b32 v12, v34, v38, v39
	v_and_b32_e32 v30, 0xf000, v30
	v_and_b32_e32 v31, 0xf0000, v31
	v_and_b32_e32 v42, 0xf000000, v42
	v_and_b32_e32 v49, 0xf0000000, v49
	v_or3_b32 v12, v12, v40, v41
	v_lshlrev_b32_e32 v32, 20, v32
	v_lshlrev_b32_e32 v33, 24, v33
	v_or3_b32 v7, v7, v30, v31
	v_or3_b32 v30, v12, v42, v49
	v_mul_f32_e32 v12, v6, v43
	v_rndne_f32_e32 v35, v35
	v_and_b32_e32 v32, 0xf00000, v32
	v_and_b32_e32 v33, 0xf000000, v33
	v_rndne_f32_e32 v12, v12
	v_or3_b32 v31, v7, v32, v33
	v_cvt_i32_f32_e32 v7, v35
	v_cvt_i32_f32_e32 v12, v12
	v_mul_f32_e32 v33, v6, v44
	v_mul_f32_e32 v5, v6, v5
	v_rndne_f32_e32 v33, v33
	v_rndne_f32_e32 v5, v5
	v_cvt_i32_f32_e32 v33, v33
	v_cvt_i32_f32_e32 v5, v5
	v_add_u32_e32 v27, 8, v7
	v_add_u32_e32 v32, 8, v12
	v_lshrrev_b32_e32 v27, 4, v27
	v_and_b32_e32 v32, 0xf0, v32
	v_and_or_b32 v27, v27, 15, v32
	v_lshl_add_u32 v32, v33, 4, v122
	v_lshl_add_u32 v34, v5, 8, v123
	v_and_b32_e32 v32, 0xf00, v32
	v_and_b32_e32 v34, 0xf000, v34
	v_mul_f32_e32 v35, v6, v45
	v_or3_b32 v27, v27, v32, v34
	v_mul_f32_e32 v34, v6, v46
	v_rndne_f32_e32 v35, v35
	v_rndne_f32_e32 v34, v34
	v_cvt_i32_f32_e32 v35, v35
	v_cvt_i32_f32_e32 v34, v34
	v_mul_f32_e32 v37, v6, v47
	v_mul_f32_e32 v6, v6, v48
	v_rndne_f32_e32 v37, v37
	v_rndne_f32_e32 v6, v6
	v_cvt_i32_f32_e32 v37, v37
	v_cvt_i32_f32_e32 v6, v6
	v_lshl_add_u32 v32, v35, 12, v124
	v_lshl_add_u32 v36, v34, 16, v125
	v_and_b32_e32 v32, 0xf0000, v32
	v_and_b32_e32 v36, 0xf00000, v36
	v_and_b32_e32 v7, 15, v7
	v_lshlrev_b32_e32 v12, 4, v12
	v_lshlrev_b32_e32 v33, 8, v33
	v_or3_b32 v27, v27, v32, v36
	v_lshlrev_b32_e32 v32, 20, v34
	v_and_b32_e32 v12, 0xf0, v12
	v_and_b32_e32 v33, 0xf00, v33
	v_lshlrev_b32_e32 v5, 12, v5
	v_lshlrev_b32_e32 v35, 16, v35
	v_and_b32_e32 v34, 0xf00000, v32
	v_lshl_add_u32 v32, v37, 20, v126
	v_lshlrev_b32_e32 v36, 24, v37
	v_lshl_add_u32 v37, v6, 24, v127
	v_lshl_or_b32 v6, v6, 28, v7
	v_and_b32_e32 v5, 0xf000, v5
	v_and_b32_e32 v35, 0xf0000, v35
	v_or3_b32 v6, v6, v12, v33
	v_and_b32_e32 v32, 0xf000000, v32
	v_and_b32_e32 v36, 0xf000000, v36
	v_and_b32_e32 v37, 0xf0000000, v37
	v_or3_b32 v5, v6, v5, v35
	v_cmp_gt_u32_e32 vcc, s37, v4
	v_or3_b32 v32, v27, v32, v37
	v_or3_b32 v33, v5, v34, v36
	s_bcnt1_i32_b64 s8, vcc
	v_mov_b32_e32 v5, v13
	ds_write_b128 v128, v[30:33] offset:1024
	s_and_saveexec_b64 s[6:7], s[4:5]
	v_mbcnt_lo_u32_b32 v5, s4, 0
	v_mbcnt_hi_u32_b32 v5, s5, v5
	v_add_u32_e32 v5, s8, v5
	s_or_b64 exec, exec, s[6:7]
	v_ashrrev_i32_e32 v6, 11, v4
	s_bcnt1_i32_b64 s42, s[4:5]
	v_cmp_eq_u32_e64 s[4:5], 1, v6
	v_ashrrev_i32_e32 v7, 11, v1
	s_add_i32 s42, s42, s8
	s_bcnt1_i32_b64 s8, s[4:5]
	v_cmp_eq_u32_e64 s[6:7], 1, v7
	s_add_i32 s43, s42, s8
	s_and_saveexec_b64 s[8:9], s[6:7]
; __device__ __forceinline__ float bf_lo(unsigned u) { return __uint_as_float(u << 16); }
; __device__ __forceinline__ float bf_hi(unsigned u) { return __uint_as_float(u & 0xffff0000u); }
; __device__ __forceinline__ void p3_token(const Params& p, int tok, int lane, unsigned* rec, float& sh, int& hs8) {
;     ...
;         const u32x4 a = *(const u32x4*)(H + (size_t)tok * DM + lane * 16), b = *(const u32x4*)(H + (size_t)tok * DM + lane * 16 + 8);
;         const unsigned hw[8] = {a.x, a.y, a.z, a.w, b.x, b.y, b.z, b.w};
;         float hv[16];
;         float mx = 0.f;
; #pragma unroll
;         for (int i = 0; i < 8; i++) { hv[2 * i] = bf_lo(hw[i]); hv[2 * i + 1] = bf_hi(hw[i]); mx = fmaxf(mx, fmaxf(fabsf(hv[2 * i]), fabsf(hv[2 * i + 1]))); }
;         mx = wave_max(mx);
;     ...
;     const int e0 = eidx[(size_t)tok * 128 + lane], e1 = eidx[(size_t)tok * 128 + 64 + lane];
;     const float g0 = gwp[(size_t)tok * 128 + lane], g1 = gwp[(size_t)tok * 128 + 64 + lane];
;     const int k0 = e0 >> 11, k1 = e1 >> 11;
;     int pos0 = 0, pos1 = 0, base = 0;
; #pragma unroll
;     for (int v = 0; v < 8; v++) {
;         const unsigned long long m0 = __ballot(k0 == v), m1 = __ballot(k1 == v);
;         const int c0 = __popcll(m0);
;         const int r0 = __builtin_amdgcn_mbcnt_hi((unsigned)(m0 >> 32), __builtin_amdgcn_mbcnt_lo((unsigned)m0, 0u));
;         const int r1 = __builtin_amdgcn_mbcnt_hi((unsigned)(m1 >> 32), __builtin_amdgcn_mbcnt_lo((unsigned)m1, 0u));
;         pos0 = (k0 == v) ? base + r0 : pos0;
;         pos1 = (k1 == v) ? base + c0 + r1 : pos1;
;         base += c0 + __popcll(m1);
;     }
;     const float* tsc = (const float*)(p.ws + OFF_UB + 33554432);
;     const f32x2 s0 = *(const f32x2*)(tsc + 2 * e0), s1 = *(const f32x2*)(tsc + 2 * e1);
;     rec[pos0] = (unsigned)e0; rec[pos1] = (unsigned)e1;
;     rec[128 + pos0] = __float_as_uint(g0 * s0[1]); rec[128 + pos1] = __float_as_uint(g1 * s1[1]);
;     rec[512 + pos0] = __float_as_uint(sh * s0[0]); rec[512 + pos1] = __float_as_uint(sh * s1[0]);
	v_mbcnt_lo_u32_b32 v5, s6, 0
	v_mbcnt_hi_u32_b32 v5, s7, v5
	v_add_u32_e32 v5, s43, v5
	s_or_b64 exec, exec, s[8:9]
	s_bcnt1_i32_b64 s6, s[6:7]
	s_add_i32 s43, s43, s6
	v_cmp_eq_u32_e64 s[6:7], 2, v6
	s_bcnt1_i32_b64 s10, s[6:7]
	v_cmp_eq_u32_e64 s[8:9], 2, v7
	s_add_i32 s44, s43, s10
	s_and_saveexec_b64 s[10:11], s[8:9]
	v_mbcnt_lo_u32_b32 v5, s8, 0
	v_mbcnt_hi_u32_b32 v5, s9, v5
	v_add_u32_e32 v5, s44, v5
	s_or_b64 exec, exec, s[10:11]
	s_bcnt1_i32_b64 s8, s[8:9]
	s_add_i32 s44, s44, s8
	v_cmp_eq_u32_e64 s[8:9], 3, v6
	s_bcnt1_i32_b64 s12, s[8:9]
	v_cmp_eq_u32_e64 s[10:11], 3, v7
	s_add_i32 s45, s44, s12
	s_and_saveexec_b64 s[12:13], s[10:11]
	v_mbcnt_lo_u32_b32 v5, s10, 0
	v_mbcnt_hi_u32_b32 v5, s11, v5
	v_add_u32_e32 v5, s45, v5
	s_or_b64 exec, exec, s[12:13]
	s_bcnt1_i32_b64 s10, s[10:11]
	s_add_i32 s45, s45, s10
	v_cmp_eq_u32_e64 s[10:11], 4, v6
	s_bcnt1_i32_b64 s14, s[10:11]
	v_cmp_eq_u32_e64 s[12:13], 4, v7
	s_add_i32 s46, s45, s14
	s_and_saveexec_b64 s[14:15], s[12:13]
	v_mbcnt_lo_u32_b32 v5, s12, 0
	v_mbcnt_hi_u32_b32 v5, s13, v5
	v_add_u32_e32 v5, s46, v5
	s_or_b64 exec, exec, s[14:15]
	s_bcnt1_i32_b64 s12, s[12:13]
	s_add_i32 s46, s46, s12
	v_cmp_eq_u32_e64 s[12:13], 5, v6
	s_bcnt1_i32_b64 s16, s[12:13]
	v_cmp_eq_u32_e64 s[14:15], 5, v7
	s_add_i32 s47, s46, s16
	s_and_saveexec_b64 s[16:17], s[14:15]
	v_mbcnt_lo_u32_b32 v5, s14, 0
	v_mbcnt_hi_u32_b32 v5, s15, v5
	v_add_u32_e32 v5, s47, v5
	s_or_b64 exec, exec, s[16:17]
	s_bcnt1_i32_b64 s14, s[14:15]
	s_add_i32 s47, s47, s14
	v_cmp_eq_u32_e64 s[14:15], 6, v6
	s_bcnt1_i32_b64 s18, s[14:15]
	v_cmp_eq_u32_e64 s[16:17], 6, v7
	s_add_i32 s48, s47, s18
	s_and_saveexec_b64 s[18:19], s[16:17]
	v_mbcnt_lo_u32_b32 v5, s16, 0
	v_mbcnt_hi_u32_b32 v5, s17, v5
	v_add_u32_e32 v5, s48, v5
	s_or_b64 exec, exec, s[18:19]
	s_bcnt1_i32_b64 s16, s[16:17]
	s_add_i32 s48, s48, s16
	v_cmp_eq_u32_e64 s[16:17], 7, v6
	v_cmp_eq_u32_e64 s[18:19], 7, v7
	s_and_saveexec_b64 s[34:35], s[18:19]
	s_bcnt1_i32_b64 s49, s[16:17]
	v_mbcnt_lo_u32_b32 v5, s18, 0
	s_add_i32 s49, s48, s49
	v_mbcnt_hi_u32_b32 v5, s19, v5
	v_add_u32_e32 v5, s49, v5
	s_or_b64 exec, exec, s[34:35]
	v_or_b32_e32 v30, 1, v8
	v_ashrrev_i32_e32 v31, 31, v30
	v_lshlrev_b64 v[32:33], 11, v[30:31]
	v_lshl_add_u64 v[6:7], v[20:21], 0, v[32:33]
	global_load_dwordx4 v[34:37], v[6:7], off
	global_load_dwordx4 v[38:41], v[6:7], off offset:16
	v_mbcnt_lo_u32_b32 v7, s16, 0
	v_lshlrev_b32_e32 v6, 1, v4
	v_mbcnt_lo_u32_b32 v43, s12, 0
	v_lshlrev_b32_e32 v42, 1, v1
	v_mbcnt_hi_u32_b32 v51, s17, v7
	v_ashrrev_i32_e32 v7, 31, v6
	v_mbcnt_lo_u32_b32 v44, s10, 0
	v_mbcnt_lo_u32_b32 v45, s8, 0
	v_mbcnt_hi_u32_b32 v52, s13, v43
	v_ashrrev_i32_e32 v43, 31, v42
	v_lshl_add_u64 v[6:7], v[6:7], 2, s[26:27]
	v_mbcnt_hi_u32_b32 v53, s11, v44
	v_mbcnt_hi_u32_b32 v54, s9, v45
	v_lshl_add_u64 v[42:43], v[42:43], 2, s[26:27]
	global_load_dwordx2 v[44:45], v[6:7], off
	global_load_dwordx2 v[46:47], v[42:43], off
	v_mbcnt_lo_u32_b32 v48, s6, 0
	v_mbcnt_lo_u32_b32 v49, s4, 0
	v_mbcnt_lo_u32_b32 v50, vcc_lo, 0
	v_mbcnt_hi_u32_b32 v6, s7, v48
	v_mbcnt_hi_u32_b32 v7, s5, v49
	v_mbcnt_hi_u32_b32 v42, vcc_hi, v50
	v_add_u32_e32 v43, s48, v51
	v_add_u32_e32 v7, s42, v7
	v_cndmask_b32_e32 v42, 0, v42, vcc
	v_add_u32_e32 v6, s43, v6
	v_cndmask_b32_e64 v7, v42, v7, s[4:5]
	v_cndmask_b32_e64 v6, v7, v6, s[6:7]
	v_mbcnt_lo_u32_b32 v27, s14, 0
	v_mbcnt_hi_u32_b32 v27, s15, v27
	v_add_u32_e32 v27, s47, v27
	v_lshl_add_u32 v5, v5, 2, v11
	v_mul_f32_e32 v12, 0x3c09ae41, v0
	v_mov_b32_e32 v0, 0
	s_waitcnt vmcnt(3)
	v_lshlrev_b32_e32 v48, 16, v34
	v_and_b32_e32 v34, 0xffff0000, v34
	v_lshlrev_b32_e32 v49, 16, v35
	v_and_b32_e32 v35, 0xffff0000, v35
	v_lshlrev_b32_e32 v50, 16, v36
	v_and_b32_e32 v36, 0xffff0000, v36
	v_lshlrev_b32_e32 v51, 16, v37
	v_and_b32_e32 v55, 0xffff0000, v37
	s_waitcnt vmcnt(2)
	v_lshlrev_b32_e32 v56, 16, v38
	v_and_b32_e32 v57, 0xffff0000, v38
	v_lshlrev_b32_e32 v58, 16, v39
	v_and_b32_e32 v59, 0xffff0000, v39
	v_max_f32_e64 v37, |v34|, |v34|
	v_max_f32_e64 v38, |v48|, |v48|
	v_max_f32_e64 v39, |v35|, |v35|
	v_max_f32_e64 v62, |v49|, |v49|
	v_max_f32_e64 v63, |v36|, |v36|
	v_max_f32_e64 v64, |v50|, |v50|
	v_max_f32_e64 v65, |v55|, |v55|
	v_max_f32_e64 v66, |v51|, |v51|
	v_max_f32_e32 v37, v38, v37
	v_max_f32_e32 v38, v62, v39
	v_lshlrev_b32_e32 v60, 16, v40
	v_and_b32_e32 v40, 0xffff0000, v40
	v_lshlrev_b32_e32 v61, 16, v41
	v_and_b32_e32 v41, 0xffff0000, v41
	v_max_f32_e64 v67, |v57|, |v57|
	v_max_f32_e64 v68, |v56|, |v56|
	v_max_f32_e64 v69, |v59|, |v59|
	v_max_f32_e64 v70, |v58|, |v58|
	v_max_f32_e32 v39, v64, v63
	v_max_f32_e32 v62, v66, v65
	v_max3_f32 v37, v37, 0, v38
	v_max_f32_e64 v71, |v40|, |v40|
	v_max_f32_e64 v72, |v60|, |v60|
	v_max_f32_e64 v73, |v41|, |v41|
	v_max_f32_e64 v74, |v61|, |v61|
	v_max_f32_e32 v63, v68, v67
	v_max_f32_e32 v64, v70, v69
	v_max3_f32 v37, v37, v39, v62
	v_max_f32_e32 v65, v72, v71
	v_max_f32_e32 v66, v74, v73
	v_max3_f32 v37, v37, v63, v64
	v_max3_f32 v37, v37, v65, v66
	ds_bpermute_b32 v38, v112, v37
	v_add_u32_e32 v39, s46, v52
	v_add_u32_e32 v52, s45, v53
	v_add_u32_e32 v53, s44, v54
	v_cndmask_b32_e64 v6, v6, v53, s[8:9]
	s_waitcnt lgkmcnt(0)
	v_max_f32_e32 v38, v38, v38
	v_max_f32_e32 v37, v37, v38
	ds_bpermute_b32 v38, v113, v37
	v_cndmask_b32_e64 v6, v6, v52, s[10:11]
	v_cndmask_b32_e64 v6, v6, v39, s[12:13]
	v_cndmask_b32_e64 v6, v6, v27, s[14:15]
	v_cndmask_b32_e64 v6, v6, v43, s[16:17]
	s_waitcnt lgkmcnt(0)
	v_max_f32_e32 v38, v38, v38
	v_max_f32_e32 v37, v37, v38
	ds_bpermute_b32 v38, v114, v37
	v_lshl_add_u32 v6, v6, 2, v11
	ds_write_b32 v6, v4
	ds_write_b32 v5, v1
	s_waitcnt vmcnt(1)
	v_mul_f32_e32 v1, v2, v45
	s_waitcnt lgkmcnt(2)
; __device__ __forceinline__ void p3_token(const Params& p, int tok, int lane, unsigned* rec, float& sh, int& hs8) {
;     ...
;         mx = wave_max(mx);
;         const float inv = mx > 0.f ? 119.f / mx : 0.f;
;         sh = mx * (1.f / 119.f);
;         unsigned qh[4] = {0u, 0u, 0u, 0u};
; #pragma unroll
;         for (int e = 0; e < 16; e++) {
;             const int qi = (int)rintf(hv[e] * inv);
;             const int hh = (qi + 8) >> 4, hl = qi - 16 * hh;
;             qh[(e >> 3) * 2] |= (unsigned)(hh & 15) << ((e & 7) * 4);
;             qh[(e >> 3) * 2 + 1] |= (unsigned)(hl & 15) << ((e & 7) * 4);
;         }
;         hs8 = 0;
;         *(u32x4*)(rec + 256 + lane * 4) = (u32x4){qh[0], qh[1], qh[2], qh[3]};
;     }
;     const int e0 = eidx[(size_t)tok * 128 + lane], e1 = eidx[(size_t)tok * 128 + 64 + lane];
;     const float g0 = gwp[(size_t)tok * 128 + lane], g1 = gwp[(size_t)tok * 128 + 64 + lane];
;     const int k0 = e0 >> 11, k1 = e1 >> 11;
	v_max_f32_e32 v7, v38, v38
	v_max_f32_e32 v7, v37, v7
	ds_bpermute_b32 v37, v115, v7
	s_waitcnt vmcnt(0)
	v_mul_f32_e32 v2, v3, v47
	v_mul_f32_e32 v3, v12, v44
	ds_write_b32 v6, v1 offset:512
	ds_write_b32 v5, v2 offset:512
	ds_write_b32 v6, v3 offset:2048
	v_mul_f32_e32 v12, v12, v46
	s_waitcnt lgkmcnt(3)
	v_max_f32_e32 v4, v37, v37
	v_max_f32_e32 v4, v7, v4
	ds_bpermute_b32 v7, v116, v4
	ds_write_b32 v5, v12 offset:2048
	s_waitcnt lgkmcnt(1)
	v_max_f32_e32 v7, v7, v7
	v_max_f32_e32 v4, v4, v7
	ds_bpermute_b32 v7, v117, v4
	s_waitcnt lgkmcnt(0)
	v_max_f32_e32 v1, v7, v7
	v_max_f32_e32 v1, v4, v1
	v_div_scale_f32 v2, s[4:5], v1, v1, s33
	v_rcp_f32_e32 v3, v2
	v_div_scale_f32 v4, vcc, s33, v1, s33
	v_fma_f32 v5, -v2, v3, 1.0
	v_fmac_f32_e32 v3, v5, v3
	v_mul_f32_e32 v5, v4, v3
	v_fma_f32 v6, -v2, v5, v4
	v_fmac_f32_e32 v5, v6, v3
	v_fma_f32 v2, -v2, v5, v4
	v_div_fmas_f32 v2, v2, v3, v5
	v_div_fixup_f32 v2, v2, v1, s33
	v_cmp_lt_f32_e32 vcc, 0, v1
	s_nop 1
	v_cndmask_b32_e32 v12, 0, v2, vcc
	v_mul_f32_e32 v2, v12, v48
	v_mul_f32_e32 v3, v12, v34
	v_rndne_f32_e32 v2, v2
	v_rndne_f32_e32 v3, v3
	v_cvt_i32_f32_e32 v2, v2
	v_cvt_i32_f32_e32 v3, v3
	v_mul_f32_e32 v4, v12, v49
	v_mul_f32_e32 v5, v12, v35
	v_rndne_f32_e32 v4, v4
	v_add_u32_e32 v6, 8, v2
	v_and_b32_e32 v27, 15, v2
	v_add_u32_e32 v2, 8, v3
	v_lshlrev_b32_e32 v3, 4, v3
	v_cvt_i32_f32_e32 v4, v4
	v_and_b32_e32 v42, 0xf0, v3
	v_rndne_f32_e32 v3, v5
	v_cvt_i32_f32_e32 v3, v3
	v_lshl_add_u32 v7, v4, 4, v122
	v_lshlrev_b32_e32 v4, 8, v4
	v_lshrrev_b32_e32 v6, 4, v6
	v_and_b32_e32 v2, 0xf0, v2
	v_and_b32_e32 v43, 0xf00, v4
	v_lshl_add_u32 v4, v3, 8, v123
	v_and_or_b32 v2, v6, 15, v2
	v_and_b32_e32 v5, 0xf00, v7
	v_and_b32_e32 v4, 0xf000, v4
	v_mul_f32_e32 v6, v12, v50
	v_rndne_f32_e32 v6, v6
	v_or3_b32 v2, v2, v5, v4
	v_mul_f32_e32 v4, v12, v36
	v_cvt_i32_f32_e32 v6, v6
	v_rndne_f32_e32 v4, v4
	v_cvt_i32_f32_e32 v4, v4
	v_lshlrev_b32_e32 v3, 12, v3
	v_lshlrev_b32_e32 v5, 16, v6
	v_and_b32_e32 v44, 0xf000, v3
	v_lshl_add_u32 v3, v6, 12, v124
	v_and_b32_e32 v45, 0xf0000, v5
	v_lshl_add_u32 v5, v4, 16, v125
	v_and_b32_e32 v3, 0xf0000, v3
	v_and_b32_e32 v5, 0xf00000, v5
	v_or3_b32 v46, v2, v3, v5
	v_lshlrev_b32_e32 v2, 20, v4
	v_and_b32_e32 v47, 0xf00000, v2
	v_mul_f32_e32 v2, v12, v51
	v_rndne_f32_e32 v2, v2
	v_cvt_i32_f32_e32 v48, v2
	v_lshlrev_b64 v[2:3], 9, v[30:31]
	v_lshl_or_b32 v2, v10, 2, v2
	v_lshl_add_u64 v[6:7], s[20:21], 0, v[2:3]
	v_or_b32_e32 v4, 0x100, v2
	v_mov_b32_e32 v5, v3
	v_lshl_add_u64 v[34:35], s[20:21], 0, v[4:5]
	v_lshl_add_u64 v[36:37], s[24:25], 0, v[2:3]
	v_lshl_add_u64 v[38:39], s[24:25], 0, v[4:5]
	global_load_dword v2, v[6:7], off
	global_load_dword v3, v[34:35], off
	global_load_dword v4, v[36:37], off
	global_load_dword v5, v[38:39], off
	v_mul_f32_e32 v7, v12, v55
	v_rndne_f32_e32 v7, v7
	v_cvt_i32_f32_e32 v7, v7
	v_lshlrev_b32_e32 v34, 24, v48
	v_lshl_add_u32 v6, v48, 20, v126
	v_and_b32_e32 v35, 0xf000000, v34
	v_lshl_add_u32 v34, v7, 24, v127
	v_and_b32_e32 v6, 0xf000000, v6
	v_and_b32_e32 v34, 0xf0000000, v34
	v_or3_b32 v34, v46, v6, v34
	v_lshl_or_b32 v6, v7, 28, v27
	v_or3_b32 v6, v6, v42, v43
	v_or3_b32 v6, v6, v44, v45
	v_or3_b32 v35, v6, v47, v35
	v_mul_f32_e32 v6, v12, v56
	v_mul_f32_e32 v7, v12, v57
	v_rndne_f32_e32 v6, v6
	v_rndne_f32_e32 v7, v7
	v_cvt_i32_f32_e32 v6, v6
	v_cvt_i32_f32_e32 v7, v7
	v_mul_f32_e32 v37, v12, v58
	v_mul_f32_e32 v38, v12, v59
	v_rndne_f32_e32 v37, v37
	v_rndne_f32_e32 v38, v38
	v_cvt_i32_f32_e32 v37, v37
	v_cvt_i32_f32_e32 v38, v38
	v_add_u32_e32 v27, 8, v6
	v_add_u32_e32 v36, 8, v7
	v_lshrrev_b32_e32 v27, 4, v27
	v_and_b32_e32 v36, 0xf0, v36
	v_and_or_b32 v27, v27, 15, v36
	v_lshl_add_u32 v36, v37, 4, v122
	v_lshl_add_u32 v39, v38, 8, v123
	v_and_b32_e32 v36, 0xf00, v36
	v_and_b32_e32 v39, 0xf000, v39
	v_mul_f32_e32 v42, v12, v60
	v_or3_b32 v27, v27, v36, v39
	v_mul_f32_e32 v39, v12, v40
	v_rndne_f32_e32 v42, v42
	v_rndne_f32_e32 v39, v39
	v_cvt_i32_f32_e32 v42, v42
	v_cvt_i32_f32_e32 v39, v39
	v_mul_f32_e32 v43, v12, v61
	v_mul_f32_e32 v12, v12, v41
	v_rndne_f32_e32 v12, v12
	v_rndne_f32_e32 v43, v43
	v_cvt_i32_f32_e32 v12, v12
	v_lshlrev_b32_e32 v36, 12, v38
	v_cvt_i32_f32_e32 v43, v43
	v_and_b32_e32 v38, 0xf000, v36
	v_lshl_add_u32 v36, v42, 12, v124
	v_lshlrev_b32_e32 v40, 16, v42
	v_lshl_add_u32 v42, v39, 16, v125
	v_and_b32_e32 v6, 15, v6
	v_lshlrev_b32_e32 v7, 4, v7
	v_lshlrev_b32_e32 v37, 8, v37
	v_and_b32_e32 v36, 0xf0000, v36
	v_and_b32_e32 v42, 0xf00000, v42
	v_and_b32_e32 v7, 0xf0, v7
	v_and_b32_e32 v37, 0xf00, v37
	v_or3_b32 v27, v27, v36, v42
	v_lshlrev_b32_e32 v36, 20, v39
	v_lshl_or_b32 v6, v12, 28, v6
	v_and_b32_e32 v40, 0xf0000, v40
	v_and_b32_e32 v39, 0xf00000, v36
	v_lshl_add_u32 v36, v43, 20, v126
	v_lshlrev_b32_e32 v41, 24, v43
	v_lshl_add_u32 v42, v12, 24, v127
	v_or3_b32 v6, v6, v7, v37
	v_and_b32_e32 v36, 0xf000000, v36
	v_and_b32_e32 v41, 0xf000000, v41
	v_and_b32_e32 v42, 0xf0000000, v42
	v_or3_b32 v6, v6, v38, v40
	v_or3_b32 v36, v27, v36, v42
	v_or3_b32 v37, v6, v39, v41
	ds_write_b128 v128, v[34:37] offset:3584
	s_waitcnt vmcnt(3)
	v_cmp_gt_u32_e32 vcc, s37, v2
	s_waitcnt vmcnt(2)
; __device__ __forceinline__ void p3_token(const Params& p, int tok, int lane, unsigned* rec, float& sh, int& hs8) {
;     ...
;     const int k0 = e0 >> 11, k1 = e1 >> 11;
;     int pos0 = 0, pos1 = 0, base = 0;
; #pragma unroll
;     for (int v = 0; v < 8; v++) {
;         const unsigned long long m0 = __ballot(k0 == v), m1 = __ballot(k1 == v);
;         const int c0 = __popcll(m0);
;         const int r0 = __builtin_amdgcn_mbcnt_hi((unsigned)(m0 >> 32), __builtin_amdgcn_mbcnt_lo((unsigned)m0, 0u));
;         const int r1 = __builtin_amdgcn_mbcnt_hi((unsigned)(m1 >> 32), __builtin_amdgcn_mbcnt_lo((unsigned)m1, 0u));
;         pos0 = (k0 == v) ? base + r0 : pos0;
;         pos1 = (k1 == v) ? base + c0 + r1 : pos1;
;         base += c0 + __popcll(m1);
;     }
;     const float* tsc = (const float*)(p.ws + OFF_UB + 33554432);
;     const f32x2 s0 = *(const f32x2*)(tsc + 2 * e0), s1 = *(const f32x2*)(tsc + 2 * e1);
;     rec[pos0] = (unsigned)e0; rec[pos1] = (unsigned)e1;
;     rec[128 + pos0] = __float_as_uint(g0 * s0[1]); rec[128 + pos1] = __float_as_uint(g1 * s1[1]);
;     rec[512 + pos0] = __float_as_uint(sh * s0[0]); rec[512 + pos1] = __float_as_uint(sh * s1[0]);
; }
	v_cmp_gt_u32_e64 s[4:5], s37, v3
	s_bcnt1_i32_b64 s8, vcc
	s_and_saveexec_b64 s[6:7], s[4:5]
	v_mbcnt_lo_u32_b32 v0, s4, 0
	v_mbcnt_hi_u32_b32 v0, s5, v0
	v_add_u32_e32 v0, s8, v0
	s_or_b64 exec, exec, s[6:7]
	v_ashrrev_i32_e32 v6, 11, v2
	s_bcnt1_i32_b64 s42, s[4:5]
	v_cmp_eq_u32_e64 s[4:5], 1, v6
	v_ashrrev_i32_e32 v7, 11, v3
	s_add_i32 s42, s42, s8
	s_bcnt1_i32_b64 s8, s[4:5]
	v_cmp_eq_u32_e64 s[6:7], 1, v7
	s_add_i32 s43, s42, s8
	s_and_saveexec_b64 s[8:9], s[6:7]
	v_mbcnt_lo_u32_b32 v0, s6, 0
	v_mbcnt_hi_u32_b32 v0, s7, v0
	v_add_u32_e32 v0, s43, v0
	s_or_b64 exec, exec, s[8:9]
	s_bcnt1_i32_b64 s6, s[6:7]
	s_add_i32 s43, s43, s6
	v_cmp_eq_u32_e64 s[6:7], 2, v6
	s_bcnt1_i32_b64 s10, s[6:7]
	v_cmp_eq_u32_e64 s[8:9], 2, v7
	s_add_i32 s44, s43, s10
	s_and_saveexec_b64 s[10:11], s[8:9]
	v_mbcnt_lo_u32_b32 v0, s8, 0
	v_mbcnt_hi_u32_b32 v0, s9, v0
	v_add_u32_e32 v0, s44, v0
	s_or_b64 exec, exec, s[10:11]
	s_bcnt1_i32_b64 s8, s[8:9]
	s_add_i32 s44, s44, s8
	v_cmp_eq_u32_e64 s[8:9], 3, v6
	s_bcnt1_i32_b64 s12, s[8:9]
	v_cmp_eq_u32_e64 s[10:11], 3, v7
	s_add_i32 s45, s44, s12
	s_and_saveexec_b64 s[12:13], s[10:11]
	v_mbcnt_lo_u32_b32 v0, s10, 0
	v_mbcnt_hi_u32_b32 v0, s11, v0
	v_add_u32_e32 v0, s45, v0
	s_or_b64 exec, exec, s[12:13]
	s_bcnt1_i32_b64 s10, s[10:11]
	s_add_i32 s45, s45, s10
	v_cmp_eq_u32_e64 s[10:11], 4, v6
	s_bcnt1_i32_b64 s14, s[10:11]
	v_cmp_eq_u32_e64 s[12:13], 4, v7
	s_add_i32 s46, s45, s14
	s_and_saveexec_b64 s[14:15], s[12:13]
	v_mbcnt_lo_u32_b32 v0, s12, 0
	v_mbcnt_hi_u32_b32 v0, s13, v0
	v_add_u32_e32 v0, s46, v0
	s_or_b64 exec, exec, s[14:15]
	s_bcnt1_i32_b64 s12, s[12:13]
	s_add_i32 s46, s46, s12
	v_cmp_eq_u32_e64 s[12:13], 5, v6
	s_bcnt1_i32_b64 s16, s[12:13]
	v_cmp_eq_u32_e64 s[14:15], 5, v7
	s_add_i32 s47, s46, s16
	s_and_saveexec_b64 s[16:17], s[14:15]
	v_mbcnt_lo_u32_b32 v0, s14, 0
	v_mbcnt_hi_u32_b32 v0, s15, v0
	v_add_u32_e32 v0, s47, v0
	s_or_b64 exec, exec, s[16:17]
	s_bcnt1_i32_b64 s14, s[14:15]
	s_add_i32 s47, s47, s14
	v_cmp_eq_u32_e64 s[14:15], 6, v6
	s_bcnt1_i32_b64 s18, s[14:15]
	v_cmp_eq_u32_e64 s[16:17], 6, v7
	s_add_i32 s48, s47, s18
	s_and_saveexec_b64 s[18:19], s[16:17]
	v_mbcnt_lo_u32_b32 v0, s16, 0
	v_mbcnt_hi_u32_b32 v0, s17, v0
	v_add_u32_e32 v0, s48, v0
	s_or_b64 exec, exec, s[18:19]
	s_bcnt1_i32_b64 s16, s[16:17]
	s_add_i32 s48, s48, s16
	v_cmp_eq_u32_e64 s[16:17], 7, v6
	v_cmp_eq_u32_e64 s[18:19], 7, v7
	s_and_saveexec_b64 s[34:35], s[18:19]
	s_bcnt1_i32_b64 s49, s[16:17]
	v_mbcnt_lo_u32_b32 v0, s18, 0
	s_add_i32 s49, s48, s49
	v_mbcnt_hi_u32_b32 v0, s19, v0
	v_add_u32_e32 v0, s49, v0
	s_or_b64 exec, exec, s[34:35]
	v_lshlrev_b32_e32 v6, 1, v2
	v_ashrrev_i32_e32 v7, 31, v6
	v_lshlrev_b32_e32 v34, 1, v3
	v_lshl_add_u64 v[6:7], v[6:7], 2, s[26:27]
	v_ashrrev_i32_e32 v35, 31, v34
	v_lshl_add_u64 v[34:35], v[34:35], 2, s[26:27]
	global_load_dwordx2 v[36:37], v[6:7], off
	global_load_dwordx2 v[38:39], v[34:35], off
	v_mbcnt_lo_u32_b32 v41, s4, 0
	v_mbcnt_lo_u32_b32 v42, vcc_lo, 0
	v_mbcnt_lo_u32_b32 v40, s6, 0
	v_mbcnt_hi_u32_b32 v41, s5, v41
	v_mbcnt_hi_u32_b32 v42, vcc_hi, v42
	v_mbcnt_lo_u32_b32 v34, s8, 0
	v_mbcnt_hi_u32_b32 v40, s7, v40
	v_add_u32_e32 v41, s42, v41
	v_cndmask_b32_e32 v42, 0, v42, vcc
	v_mbcnt_lo_u32_b32 v27, s10, 0
	v_mbcnt_hi_u32_b32 v34, s9, v34
	v_add_u32_e32 v40, s43, v40
	v_cndmask_b32_e64 v41, v42, v41, s[4:5]
	v_mbcnt_lo_u32_b32 v12, s12, 0
	v_mbcnt_hi_u32_b32 v27, s11, v27
	v_add_u32_e32 v34, s44, v34
	v_cndmask_b32_e64 v40, v41, v40, s[6:7]
	v_mbcnt_lo_u32_b32 v7, s14, 0
	v_mbcnt_hi_u32_b32 v12, s13, v12
	v_add_u32_e32 v27, s45, v27
	v_cndmask_b32_e64 v34, v40, v34, s[8:9]
	v_mbcnt_lo_u32_b32 v6, s16, 0
	v_mbcnt_hi_u32_b32 v7, s15, v7
	v_add_u32_e32 v12, s46, v12
	v_cndmask_b32_e64 v27, v34, v27, s[10:11]
	v_mbcnt_hi_u32_b32 v6, s17, v6
	v_add_u32_e32 v7, s47, v7
	v_cndmask_b32_e64 v12, v27, v12, s[12:13]
	v_add_u32_e32 v6, s48, v6
	v_cndmask_b32_e64 v7, v12, v7, s[14:15]
	v_cndmask_b32_e64 v6, v7, v6, s[16:17]
	v_mul_f32_e32 v1, 0x3c09ae41, v1
	v_lshl_add_u32 v6, v6, 2, v11
	v_lshl_add_u32 v0, v0, 2, v11
	ds_write_b32 v6, v2 offset:2560
	ds_write_b32 v0, v3 offset:2560
	v_mov_b32_e32 v35, v13
	v_mov_b32_e32 v41, v13
	s_mov_b32 s5, 0
	s_waitcnt vmcnt(1)
	v_mul_f32_e32 v2, v4, v37
	s_waitcnt vmcnt(0)
	v_mul_f32_e32 v3, v5, v39
	v_mul_f32_e32 v4, v1, v36
	v_mul_f32_e32 v1, v1, v38
	ds_write_b32 v6, v2 offset:3072
	ds_write_b32 v0, v3 offset:3072
	ds_write_b32 v6, v4 offset:4608
	ds_write_b32 v0, v1 offset:4608
	ds_read_b128 v[0:3], v11
	ds_read_b128 v[4:7], v11 offset:2560
	v_mov_b32_e32 v37, v13
	v_mov_b32_e32 v39, v13
	s_waitcnt lgkmcnt(1)
	v_mov_b32_e32 v12, v0
	v_mov_b32_e32 v34, v1
	v_mov_b32_e32 v36, v3
	s_waitcnt lgkmcnt(0)
; __device__ __forceinline__ void p3_load_u(u32x2 (&ur)[4], P3Sc& sc, const unsigned char* __restrict__ UQ, const float* __restrict__ tsc,
;                                           int lane, int ul, int g, const unsigned* rec) {
; #pragma unroll
;     for (int u = 0; u < 4; u++) ur[u] = *(const u32x2*)(UQ + (size_t)rec[4 * g + u] * 512 + lane * 8);
;     sc.gm = __uint_as_float(rec[128 + 4 * g + ul]);
;     sc.su = __uint_as_float(rec[512 + 4 * g + ul]);
;     sc.sv = 1.f;
; }
; __device__ __forceinline__ void p3_load_v(u32x2 (&vr)[4], const unsigned char* __restrict__ VQ, int lane, int g, const unsigned* rec) {
; #pragma unroll
;     for (int u = 0; u < 4; u++) vr[u] = *(const u32x2*)(VQ + (size_t)rec[4 * g + u] * 512 + lane * 8);
; }
; __device__ __forceinline__ void p3_dots(const u32x2 (&ur)[4], const unsigned* rec, int lane, int (&pt)[4]) {
;     const u32x4 qh = *(const u32x4*)(rec + 256 + lane * 4);
; #pragma unroll
;     for (int u = 0; u < 4; u++) {
;         const int w0 = (int)ur[u].x, w1 = (int)ur[u].y;
;         int dh = __builtin_amdgcn_sdot8(w0, (int)qh.x, 0, false);
;         dh = __builtin_amdgcn_sdot8(w1, (int)qh.z, dh, false);
;         int dl = __builtin_amdgcn_sdot8(w0, (int)qh.y, 0, false);
;         dl = __builtin_amdgcn_sdot8(w1, (int)qh.w, dl, false);
;         pt[u] = (dh << 4) + dl;
;     }
; }
; __device__ void phaseP3(const Params& p, float* dstp, char* lds) {
;     ...
;         u32x2 ur[TPW][4];
;         u32x2 vr[TPW][4];
;         P3Sc sc[TPW];
; #pragma unroll
;         for (int k = 0; k < TPW; k++) {
;             p3_load_u(ur[k], sc[k], UQ, tsc, lane, ul, 0, recs + k * (P3_REC / 4));
;             p3_load_v(vr[k], VQ, lane, 0, recs + k * (P3_REC / 4));
;         }
;         for (int g = 0; g < 32; g++) {
; #pragma unroll
;             for (int k = 0; k < TPW; k++) {
;                 int pt[4];
;                 p3_dots(ur[k], recs + k * (P3_REC / 4), lane, pt);
;                 const P3Sc sck = sc[k];
;                 if (g + 1 < 32) p3_load_u(ur[k], sc[k], UQ, tsc, lane, ul, g + 1, recs + k * (P3_REC / 4));
;                 const float w = p3_weight(pt, lane, sh[k], hs8[k], sck);
;                 p3_axpy(vr[k], w, acc[k]);
;                 if (g + 1 < 32) p3_load_v(vr[k], VQ, lane, g + 1, recs + k * (P3_REC / 4));
	v_mov_b32_e32 v38, v5
	v_mov_b32_e32 v40, v7
	v_lshlrev_b64 v[0:1], 9, v[34:35]
	v_lshlrev_b64 v[34:35], 9, v[12:13]
	v_mov_b32_e32 v12, v2
	v_lshlrev_b64 v[2:3], 9, v[36:37]
	v_lshlrev_b64 v[36:37], 9, v[38:39]
	v_lshlrev_b64 v[38:39], 9, v[40:41]
	v_lshl_add_u64 v[40:41], v[14:15], 0, v[34:35]
	v_lshlrev_b64 v[44:45], 9, v[12:13]
	v_lshl_add_u64 v[42:43], v[14:15], 0, v[0:1]
	v_lshl_add_u64 v[46:47], v[14:15], 0, v[2:3]
	v_lshl_add_u64 v[34:35], v[16:17], 0, v[34:35]
	v_lshl_add_u64 v[0:1], v[16:17], 0, v[0:1]
	v_lshl_add_u64 v[2:3], v[16:17], 0, v[2:3]
	v_mov_b32_e32 v12, v4
	v_lshl_add_u64 v[50:51], v[14:15], 0, v[44:45]
	v_lshl_add_u64 v[44:45], v[16:17], 0, v[44:45]
	global_load_dwordx2 v[80:81], v[40:41], off
	global_load_dwordx2 v[74:75], v[42:43], off
	global_load_dwordx2 v[84:85], v[50:51], off
	global_load_dwordx2 v[82:83], v[46:47], off
	global_load_dwordx2 v[72:73], v[34:35], off
	global_load_dwordx2 v[70:71], v[0:1], off
	global_load_dwordx2 v[62:63], v[44:45], off
	global_load_dwordx2 v[58:59], v[2:3], off
	v_lshlrev_b64 v[52:53], 9, v[12:13]
	v_mov_b32_e32 v12, v6
	v_lshl_add_u64 v[0:1], v[14:15], 0, v[52:53]
	v_lshlrev_b64 v[2:3], 9, v[12:13]
	v_lshl_add_u64 v[4:5], v[14:15], 0, v[36:37]
	v_lshl_add_u64 v[48:49], v[14:15], 0, v[38:39]
	v_lshl_add_u64 v[6:7], v[14:15], 0, v[2:3]
	global_load_dwordx2 v[66:67], v[0:1], off
	global_load_dwordx2 v[60:61], v[4:5], off
	global_load_dwordx2 v[68:69], v[6:7], off
	global_load_dwordx2 v[64:65], v[48:49], off
	v_lshl_add_u64 v[0:1], v[16:17], 0, v[52:53]
	v_lshl_add_u64 v[4:5], v[16:17], 0, v[36:37]
	v_lshl_add_u64 v[2:3], v[16:17], 0, v[2:3]
	v_lshl_add_u64 v[6:7], v[16:17], 0, v[38:39]
	global_load_dwordx2 v[40:41], v[0:1], off
	global_load_dwordx2 v[38:39], v[4:5], off
	global_load_dwordx2 v[36:37], v[2:3], off
	global_load_dwordx2 v[34:35], v[6:7], off
	ds_read2st64_b32 v[76:77], v119 offset0:2 offset1:8
	ds_read2st64_b32 v[78:79], v119 offset0:12 offset1:18
	ds_read_b128 v[4:7], v128 offset:1024
	ds_read_b128 v[0:3], v128 offset:3584
	v_mov_b32_e32 v42, 0
	v_mov_b32_e32 v43, v42
	v_mov_b32_e32 v44, v42
	v_mov_b32_e32 v45, v42
	v_mov_b32_e32 v46, v42
	v_mov_b32_e32 v47, v42
	v_mov_b32_e32 v48, v42
	v_mov_b32_e32 v49, v42
	v_mov_b32_e32 v50, v42
	v_mov_b32_e32 v51, v42
	v_mov_b32_e32 v52, v42
	v_mov_b32_e32 v53, v42
	v_mov_b32_e32 v86, v42
	v_mov_b32_e32 v87, v42
	v_mov_b32_e32 v88, v42
	v_mov_b32_e32 v89, v42
	v_mov_b32_e32 v90, v42
	v_mov_b32_e32 v91, v42
	v_mov_b32_e32 v92, v42
	v_mov_b32_e32 v93, v42
	v_mov_b32_e32 v94, v42
	v_mov_b32_e32 v95, v42
	v_mov_b32_e32 v96, v42
	v_mov_b32_e32 v97, v42
	v_mov_b32_e32 v98, v42
	v_mov_b32_e32 v99, v42
	v_mov_b32_e32 v100, v42
	v_mov_b32_e32 v101, v42
	v_mov_b32_e32 v54, v42
	v_mov_b32_e32 v55, v42
	v_mov_b32_e32 v56, v42
	v_mov_b32_e32 v57, v42
	s_waitcnt vmcnt(0)
	ds_write_b64 v149, v[80:81]
	ds_write_b64 v149, v[74:75] offset:512
	ds_write_b64 v149, v[84:85] offset:1024
	ds_write_b64 v149, v[82:83] offset:1536
	ds_write_b64 v149, v[66:67] offset:2048
	ds_write_b64 v149, v[60:61] offset:2560
	ds_write_b64 v149, v[68:69] offset:3072
	ds_write_b64 v149, v[64:65] offset:3584
	s_waitcnt lgkmcnt(0)
	v_cndmask_b32_e64 v76, v76, v78, s[54:55]
	v_cndmask_b32_e64 v77, v77, v79, s[54:55]
	.p2alignl 6, 3212836864
.LBB0_1075:
	v_add_u32_e32 v134, s5, v121
	v_add_u32_e32 v135, s5, v137
	ds_read_b128 v[140:143], v134
	ds_read_b128 v[144:147], v134 offset:2560
	s_waitcnt vmcnt(8)
	ds_read_b64 v[80:81], v149
	ds_read_b64 v[74:75], v149 offset:512
	ds_read_b64 v[84:85], v149 offset:1024
	ds_read_b64 v[82:83], v149 offset:1536
	ds_read_b64 v[66:67], v149 offset:2048
	ds_read_b64 v[60:61], v149 offset:2560
	ds_read_b64 v[68:69], v149 offset:3072
	ds_read_b64 v[64:65], v149 offset:3584
	s_waitcnt lgkmcnt(0)
	v_cndmask_b32_e64 v150, v141, v140, s[58:59]
	v_cndmask_b32_e64 v151, v143, v142, s[58:59]
	v_cndmask_b32_e64 v152, v145, v144, s[58:59]
	v_cndmask_b32_e64 v153, v147, v146, s[58:59]
	v_lshl_add_u32 v150, v150, 9, v148
	v_lshl_add_u32 v151, v151, 9, v148
	v_lshl_add_u32 v152, v152, 9, v148
	v_lshl_add_u32 v153, v153, 9, v148
	v_dot8_i32_i4 v12, v80, v4, 0
	v_dot8_i32_i4 v27, v80, v5, 0
	v_dot8_i32_i4 v131, v74, v4, 0
	v_dot8_i32_i4 v132, v74, v5, 0
	v_dot8c_i32_i4_e32 v12, v81, v6
	v_dot8c_i32_i4_e32 v27, v81, v7
	v_dot8c_i32_i4_e32 v131, v75, v6
	v_dot8c_i32_i4_e32 v132, v75, v7
	v_dot8_i32_i4 v133, v84, v4, 0
	v_dot8_i32_i4 v176, v84, v5, 0
	v_dot8_i32_i4 v177, v82, v4, 0
	v_dot8_i32_i4 v178, v82, v5, 0
	v_dot8c_i32_i4_e32 v133, v85, v6
	v_dot8c_i32_i4_e32 v176, v85, v7
	v_dot8c_i32_i4_e32 v177, v83, v6
	v_dot8c_i32_i4_e32 v178, v83, v7
	v_lshl_add_u32 v27, v12, 4, v27
	v_lshl_add_u32 v131, v131, 4, v132
	v_lshl_add_u32 v132, v133, 4, v176
	v_lshl_add_u32 v133, v177, 4, v178
	v_cndmask_b32_e64 v12, v132, v27, s[0:1]
	v_cndmask_b32_e64 v27, v27, v132, s[0:1]
	v_lshl_add_u32 v140, v140, 9, v136
	v_lshl_add_u32 v141, v141, 9, v136
	v_add_u32_dpp v12, v27, v12 quad_perm:[1,0,3,2] row_mask:0xf bank_mask:0xf bound_ctrl:1
	v_cndmask_b32_e64 v27, v133, v131, s[0:1]
	v_cndmask_b32_e64 v131, v131, v133, s[0:1]
	v_lshl_add_u32 v142, v142, 9, v136
	v_lshl_add_u32 v143, v143, 9, v136
	v_add_u32_dpp v27, v131, v27 quad_perm:[1,0,3,2] row_mask:0xf bank_mask:0xf bound_ctrl:1
	v_cndmask_b32_e64 v131, v27, v12, s[2:3]
	v_cndmask_b32_e64 v12, v12, v27, s[2:3]
	s_mov_b32 m0, s56
	s_nop 0
	v_add_u32_dpp v12, v12, v131 quad_perm:[2,3,0,1] row_mask:0xf bank_mask:0xf bound_ctrl:1
	global_load_lds_dwordx4 v150, s[50:51]
	s_add_u32 m0, s56, 0x400
	v_add_u32_dpp v12, v12, v12 row_ror:4 row_mask:0xf bank_mask:0xf bound_ctrl:1
	global_load_lds_dwordx4 v151, s[50:51]
	s_waitcnt vmcnt(6)
; __device__ __forceinline__ void p3_dots(const u32x2 (&ur)[4], const unsigned* rec, int lane, int (&pt)[4]) {
;     const u32x4 qh = *(const u32x4*)(rec + 256 + lane * 4);
; #pragma unroll
;     for (int u = 0; u < 4; u++) {
;         const int w0 = (int)ur[u].x, w1 = (int)ur[u].y;
;         int dh = __builtin_amdgcn_sdot8(w0, (int)qh.x, 0, false);
;         dh = __builtin_amdgcn_sdot8(w1, (int)qh.z, dh, false);
;         int dl = __builtin_amdgcn_sdot8(w0, (int)qh.y, 0, false);
;         dl = __builtin_amdgcn_sdot8(w1, (int)qh.w, dl, false);
;         pt[u] = (dh << 4) + dl;
;     }
; }
; template <int CTRL> __device__ __forceinline__ int dpp_i(int v) { return __builtin_amdgcn_mov_dpp(v, CTRL, 0xF, 0xF, true); }
; __device__ __forceinline__ int xrow_sum_i(int v) {
;     const auto a = __builtin_amdgcn_permlane16_swap((unsigned)v, (unsigned)v, false, false);
;     v = (int)a[0] + (int)a[1];
;     const auto b = __builtin_amdgcn_permlane32_swap((unsigned)v, (unsigned)v, false, false);
;     return (int)b[0] + (int)b[1];
; }
; __device__ __forceinline__ float p3_weight(const int (&pt)[4], int lane, float sh, int hs8, const P3Sc& sc) {
;     int m2[2], m1;
;     const bool c0 = lane & 1;
; #pragma unroll
;     for (int j = 0; j < 2; j++) { const int keep = c0 ? pt[j + 2] : pt[j], send = c0 ? pt[j] : pt[j + 2]; m2[j] = keep + dpp_i<0xB1>(send); }
;     const bool c1 = lane & 2;
;     { const int keep = c1 ? m2[1] : m2[0], send = c1 ? m2[0] : m2[1]; m1 = keep + dpp_i<0x4E>(send); }
;     m1 += dpp_i<0x124>(m1);
;     m1 += dpp_i<0x128>(m1);
;     m1 = xrow_sum_i(m1);
;     const float aval = (float)(m1 - hs8) * sc.su;
;     return sc.gm * gelu_erf(aval);
; }
; __device__ __forceinline__ void p3_axpy(const u32x2 (&vr)[4], float ws, f32x2 (&acc)[8]) {
; #pragma unroll
;     for (int u = 0; u < 4; u++) {
;         const int la = ((u >> 1) & 1) | ((u & 1) << 1);
;         const float wu = __builtin_bit_cast(float, __builtin_amdgcn_readlane(__builtin_bit_cast(int, ws), la));
;         const f32x2 w2 = {wu, wu};
;         const unsigned vw[2] = {vr[u].x, vr[u].y};
; #pragma unroll
;         for (int i = 0; i < 2; i++) {
;             acc[i * 4 + 0] = __builtin_elementwise_fma(w2, __builtin_amdgcn_cvt_scalef32_pk_f32_fp4(vw[i], 1.0f, 0), acc[i * 4 + 0]);
	v_add_u32_dpp v181, v12, v12 row_ror:8 row_mask:0xf bank_mask:0xf bound_ctrl:1
	v_dot8_i32_i4 v12, v66, v0, 0
	v_dot8_i32_i4 v27, v66, v1, 0
	v_dot8_i32_i4 v131, v60, v0, 0
	v_dot8_i32_i4 v132, v60, v1, 0
	v_dot8c_i32_i4_e32 v12, v67, v2
	v_dot8c_i32_i4_e32 v27, v67, v3
	v_dot8c_i32_i4_e32 v131, v61, v2
	v_dot8c_i32_i4_e32 v132, v61, v3
	v_dot8_i32_i4 v133, v68, v0, 0
	v_dot8_i32_i4 v176, v68, v1, 0
	v_dot8_i32_i4 v177, v64, v0, 0
	v_dot8_i32_i4 v178, v64, v1, 0
	v_dot8c_i32_i4_e32 v133, v69, v2
	v_dot8c_i32_i4_e32 v176, v69, v3
	v_dot8c_i32_i4_e32 v177, v65, v2
	v_dot8c_i32_i4_e32 v178, v65, v3
	v_lshl_add_u32 v27, v12, 4, v27
	v_lshl_add_u32 v131, v131, 4, v132
	v_lshl_add_u32 v132, v133, 4, v176
	v_lshl_add_u32 v133, v177, 4, v178
	v_cndmask_b32_e64 v12, v132, v27, s[0:1]
	v_cndmask_b32_e64 v27, v27, v132, s[0:1]
	v_lshl_add_u32 v144, v144, 9, v136
	v_lshl_add_u32 v145, v145, 9, v136
	v_add_u32_dpp v12, v27, v12 quad_perm:[1,0,3,2] row_mask:0xf bank_mask:0xf bound_ctrl:1
	v_cndmask_b32_e64 v27, v133, v131, s[0:1]
	v_cndmask_b32_e64 v131, v131, v133, s[0:1]
	v_lshl_add_u32 v146, v146, 9, v136
	v_lshl_add_u32 v147, v147, 9, v136
	v_add_u32_dpp v27, v131, v27 quad_perm:[1,0,3,2] row_mask:0xf bank_mask:0xf bound_ctrl:1
	v_cndmask_b32_e64 v131, v27, v12, s[2:3]
	v_cndmask_b32_e64 v12, v12, v27, s[2:3]
	s_add_u32 m0, s56, 0x800
	v_cvt_scalef32_pk_f32_fp4 v[160:161], v72, 1.0
	v_add_u32_dpp v12, v12, v131 quad_perm:[2,3,0,1] row_mask:0xf bank_mask:0xf bound_ctrl:1
	global_load_lds_dwordx4 v152, s[50:51]
	s_add_u32 m0, s56, 0xc00
	v_add_u32_dpp v12, v12, v12 row_ror:4 row_mask:0xf bank_mask:0xf bound_ctrl:1
	global_load_lds_dwordx4 v153, s[50:51]
	v_cvt_scalef32_pk_f32_fp4 v[162:163], v72, 1.0 op_sel:[1,0,0]
	v_add_u32_dpp v12, v12, v12 row_ror:8 row_mask:0xf bank_mask:0xf bound_ctrl:1
	v_cvt_scalef32_pk_f32_fp4 v[164:165], v72, 1.0 op_sel:[0,1,0]
	v_cvt_scalef32_pk_f32_fp4 v[166:167], v72, 1.0 op_sel:[1,1,0]
	v_permlane16_swap_b32_e32 v181, v12
	v_add_u32_e32 v12, v181, v12
	v_mov_b32_e32 v27, v12
	v_cvt_scalef32_pk_f32_fp4 v[168:169], v73, 1.0
	v_cvt_scalef32_pk_f32_fp4 v[170:171], v73, 1.0 op_sel:[1,0,0]
	v_permlane32_swap_b32_e32 v12, v27
	v_add_u32_e32 v12, v27, v12
	v_cvt_f32_i32_e32 v12, v12
	v_mul_f32_e32 v12, v77, v12
	v_fma_f32 v179, |v12|, s39, 1.0
	v_rcp_f32_e32 v179, v179
	v_cmp_gt_f32_e32 vcc, 0, v12
	v_fmamk_f32 v180, v179, 0x3f07dc22, v129
	v_fmaak_f32 v180, v179, v180, 0x3f35f0e3
	v_fmaak_f32 v180, v179, v180, 0xbe11a98e
	v_fmaak_f32 v180, v179, v180, 0x3e027906
	v_mul_f32_e32 v179, v179, v180
	v_mul_f32_e32 v180, v12, v12
	v_mul_f32_e32 v180, 0xbf38aa3b, v180
	v_exp_f32_e32 v180, v180
	v_cvt_scalef32_pk_f32_fp4 v[172:173], v73, 1.0 op_sel:[0,1,0]
	v_mul_f32_e32 v179, v180, v179
	v_mul_f32_e32 v180, v12, v179
	v_fma_f32 v12, -v12, v179, v12
	v_cndmask_b32_e32 v12, v12, v180, vcc
	v_mul_f32_e32 v12, v76, v12
	ds_read2st64_b32 v[76:77], v135 offset1:6
	v_readlane_b32 s4, v12, 0
	v_cvt_scalef32_pk_f32_fp4 v[174:175], v73, 1.0 op_sel:[1,1,0]
	global_load_dwordx2 v[72:73], v140, s[52:53]
	v_pk_fma_f32 v[100:101], s[4:5], v[160:161], v[100:101] op_sel_hi:[0,1,1]
	v_pk_fma_f32 v[98:99], s[4:5], v[162:163], v[98:99] op_sel_hi:[0,1,1]
	v_pk_fma_f32 v[96:97], s[4:5], v[164:165], v[96:97] op_sel_hi:[0,1,1]
	v_pk_fma_f32 v[94:95], s[4:5], v[166:167], v[94:95] op_sel_hi:[0,1,1]
	v_pk_fma_f32 v[92:93], s[4:5], v[168:169], v[92:93] op_sel_hi:[0,1,1]
	v_pk_fma_f32 v[90:91], s[4:5], v[170:171], v[90:91] op_sel_hi:[0,1,1]
	v_pk_fma_f32 v[88:89], s[4:5], v[172:173], v[88:89] op_sel_hi:[0,1,1]
	v_pk_fma_f32 v[86:87], s[4:5], v[174:175], v[86:87] op_sel_hi:[0,1,1]
	v_readlane_b32 s4, v12, 2
	v_cvt_scalef32_pk_f32_fp4 v[160:161], v70, 1.0
	v_cvt_scalef32_pk_f32_fp4 v[162:163], v70, 1.0 op_sel:[1,0,0]
	v_pk_fma_f32 v[100:101], s[4:5], v[160:161], v[100:101] op_sel_hi:[0,1,1]
	v_cvt_scalef32_pk_f32_fp4 v[164:165], v70, 1.0 op_sel:[0,1,0]
	v_pk_fma_f32 v[98:99], s[4:5], v[162:163], v[98:99] op_sel_hi:[0,1,1]
	v_cvt_scalef32_pk_f32_fp4 v[166:167], v70, 1.0 op_sel:[1,1,0]
	v_pk_fma_f32 v[96:97], s[4:5], v[164:165], v[96:97] op_sel_hi:[0,1,1]
	v_cvt_scalef32_pk_f32_fp4 v[168:169], v71, 1.0
	v_pk_fma_f32 v[94:95], s[4:5], v[166:167], v[94:95] op_sel_hi:[0,1,1]
	v_cvt_scalef32_pk_f32_fp4 v[170:171], v71, 1.0 op_sel:[1,0,0]
	v_pk_fma_f32 v[92:93], s[4:5], v[168:169], v[92:93] op_sel_hi:[0,1,1]
	v_cvt_scalef32_pk_f32_fp4 v[172:173], v71, 1.0 op_sel:[0,1,0]
	v_pk_fma_f32 v[90:91], s[4:5], v[170:171], v[90:91] op_sel_hi:[0,1,1]
	v_cvt_scalef32_pk_f32_fp4 v[174:175], v71, 1.0 op_sel:[1,1,0]
	v_pk_fma_f32 v[88:89], s[4:5], v[172:173], v[88:89] op_sel_hi:[0,1,1]
	v_pk_fma_f32 v[86:87], s[4:5], v[174:175], v[86:87] op_sel_hi:[0,1,1]
	global_load_dwordx2 v[70:71], v141, s[52:53]
	v_readlane_b32 s4, v12, 1
	v_cvt_scalef32_pk_f32_fp4 v[160:161], v62, 1.0
	v_cvt_scalef32_pk_f32_fp4 v[162:163], v62, 1.0 op_sel:[1,0,0]
	v_pk_fma_f32 v[100:101], s[4:5], v[160:161], v[100:101] op_sel_hi:[0,1,1]
	v_cvt_scalef32_pk_f32_fp4 v[164:165], v62, 1.0 op_sel:[0,1,0]
	v_pk_fma_f32 v[98:99], s[4:5], v[162:163], v[98:99] op_sel_hi:[0,1,1]
	v_cvt_scalef32_pk_f32_fp4 v[166:167], v62, 1.0 op_sel:[1,1,0]
	v_pk_fma_f32 v[96:97], s[4:5], v[164:165], v[96:97] op_sel_hi:[0,1,1]
	v_cvt_scalef32_pk_f32_fp4 v[168:169], v63, 1.0
	v_pk_fma_f32 v[94:95], s[4:5], v[166:167], v[94:95] op_sel_hi:[0,1,1]
	v_cvt_scalef32_pk_f32_fp4 v[170:171], v63, 1.0 op_sel:[1,0,0]
	v_pk_fma_f32 v[92:93], s[4:5], v[168:169], v[92:93] op_sel_hi:[0,1,1]
	v_cvt_scalef32_pk_f32_fp4 v[172:173], v63, 1.0 op_sel:[0,1,0]
	v_pk_fma_f32 v[90:91], s[4:5], v[170:171], v[90:91] op_sel_hi:[0,1,1]
	v_cvt_scalef32_pk_f32_fp4 v[174:175], v63, 1.0 op_sel:[1,1,0]
	v_pk_fma_f32 v[88:89], s[4:5], v[172:173], v[88:89] op_sel_hi:[0,1,1]
	v_pk_fma_f32 v[86:87], s[4:5], v[174:175], v[86:87] op_sel_hi:[0,1,1]
	global_load_dwordx2 v[62:63], v142, s[52:53]
	v_readlane_b32 s4, v12, 3
	v_cvt_scalef32_pk_f32_fp4 v[160:161], v58, 1.0
	v_cvt_scalef32_pk_f32_fp4 v[162:163], v58, 1.0 op_sel:[1,0,0]
	v_pk_fma_f32 v[100:101], s[4:5], v[160:161], v[100:101] op_sel_hi:[0,1,1]
	v_cvt_scalef32_pk_f32_fp4 v[164:165], v58, 1.0 op_sel:[0,1,0]
	v_pk_fma_f32 v[98:99], s[4:5], v[162:163], v[98:99] op_sel_hi:[0,1,1]
	v_cvt_scalef32_pk_f32_fp4 v[166:167], v58, 1.0 op_sel:[1,1,0]
	v_pk_fma_f32 v[96:97], s[4:5], v[164:165], v[96:97] op_sel_hi:[0,1,1]
	v_cvt_scalef32_pk_f32_fp4 v[168:169], v59, 1.0
	v_pk_fma_f32 v[94:95], s[4:5], v[166:167], v[94:95] op_sel_hi:[0,1,1]
	v_cvt_scalef32_pk_f32_fp4 v[170:171], v59, 1.0 op_sel:[1,0,0]
	v_pk_fma_f32 v[92:93], s[4:5], v[168:169], v[92:93] op_sel_hi:[0,1,1]
	v_cvt_scalef32_pk_f32_fp4 v[172:173], v59, 1.0 op_sel:[0,1,0]
	v_pk_fma_f32 v[90:91], s[4:5], v[170:171], v[90:91] op_sel_hi:[0,1,1]
	v_cvt_scalef32_pk_f32_fp4 v[174:175], v59, 1.0 op_sel:[1,1,0]
	v_pk_fma_f32 v[88:89], s[4:5], v[172:173], v[88:89] op_sel_hi:[0,1,1]
	v_pk_fma_f32 v[86:87], s[4:5], v[174:175], v[86:87] op_sel_hi:[0,1,1]
	global_load_dwordx2 v[58:59], v143, s[52:53]
	s_waitcnt vmcnt(11)
; __device__ __forceinline__ void p3_axpy(const u32x2 (&vr)[4], float ws, f32x2 (&acc)[8]) {
; #pragma unroll
;     for (int u = 0; u < 4; u++) {
;         const int la = ((u >> 1) & 1) | ((u & 1) << 1);
;         const float wu = __builtin_bit_cast(float, __builtin_amdgcn_readlane(__builtin_bit_cast(int, ws), la));
;         const f32x2 w2 = {wu, wu};
;         const unsigned vw[2] = {vr[u].x, vr[u].y};
; #pragma unroll
;         for (int i = 0; i < 2; i++) {
;             acc[i * 4 + 0] = __builtin_elementwise_fma(w2, __builtin_amdgcn_cvt_scalef32_pk_f32_fp4(vw[i], 1.0f, 0), acc[i * 4 + 0]);
;             acc[i * 4 + 1] = __builtin_elementwise_fma(w2, __builtin_amdgcn_cvt_scalef32_pk_f32_fp4(vw[i], 1.0f, 1), acc[i * 4 + 1]);
;             acc[i * 4 + 2] = __builtin_elementwise_fma(w2, __builtin_amdgcn_cvt_scalef32_pk_f32_fp4(vw[i], 1.0f, 2), acc[i * 4 + 2]);
;             acc[i * 4 + 3] = __builtin_elementwise_fma(w2, __builtin_amdgcn_cvt_scalef32_pk_f32_fp4(vw[i], 1.0f, 3), acc[i * 4 + 3]);
;         }
;     }
	v_readlane_b32 s4, v12, 16
	v_cvt_scalef32_pk_f32_fp4 v[160:161], v40, 1.0
	v_cvt_scalef32_pk_f32_fp4 v[162:163], v40, 1.0 op_sel:[1,0,0]
	v_pk_fma_f32 v[52:53], s[4:5], v[160:161], v[52:53] op_sel_hi:[0,1,1]
	v_cvt_scalef32_pk_f32_fp4 v[164:165], v40, 1.0 op_sel:[0,1,0]
	v_pk_fma_f32 v[50:51], s[4:5], v[162:163], v[50:51] op_sel_hi:[0,1,1]
	v_cvt_scalef32_pk_f32_fp4 v[166:167], v40, 1.0 op_sel:[1,1,0]
	v_pk_fma_f32 v[48:49], s[4:5], v[164:165], v[48:49] op_sel_hi:[0,1,1]
	v_cvt_scalef32_pk_f32_fp4 v[168:169], v41, 1.0
	v_pk_fma_f32 v[46:47], s[4:5], v[166:167], v[46:47] op_sel_hi:[0,1,1]
	v_cvt_scalef32_pk_f32_fp4 v[170:171], v41, 1.0 op_sel:[1,0,0]
	v_pk_fma_f32 v[44:45], s[4:5], v[168:169], v[44:45] op_sel_hi:[0,1,1]
	v_cvt_scalef32_pk_f32_fp4 v[172:173], v41, 1.0 op_sel:[0,1,0]
	v_pk_fma_f32 v[42:43], s[4:5], v[170:171], v[42:43] op_sel_hi:[0,1,1]
	v_cvt_scalef32_pk_f32_fp4 v[174:175], v41, 1.0 op_sel:[1,1,0]
	v_pk_fma_f32 v[54:55], s[4:5], v[172:173], v[54:55] op_sel_hi:[0,1,1]
	v_pk_fma_f32 v[56:57], s[4:5], v[174:175], v[56:57] op_sel_hi:[0,1,1]
	global_load_dwordx2 v[40:41], v144, s[52:53]
	s_waitcnt vmcnt(11)
	v_readlane_b32 s4, v12, 18
	v_cvt_scalef32_pk_f32_fp4 v[160:161], v38, 1.0
	v_cvt_scalef32_pk_f32_fp4 v[162:163], v38, 1.0 op_sel:[1,0,0]
	v_pk_fma_f32 v[52:53], s[4:5], v[160:161], v[52:53] op_sel_hi:[0,1,1]
	v_cvt_scalef32_pk_f32_fp4 v[164:165], v38, 1.0 op_sel:[0,1,0]
	v_pk_fma_f32 v[50:51], s[4:5], v[162:163], v[50:51] op_sel_hi:[0,1,1]
	v_cvt_scalef32_pk_f32_fp4 v[166:167], v38, 1.0 op_sel:[1,1,0]
	v_pk_fma_f32 v[48:49], s[4:5], v[164:165], v[48:49] op_sel_hi:[0,1,1]
	v_cvt_scalef32_pk_f32_fp4 v[168:169], v39, 1.0
	v_pk_fma_f32 v[46:47], s[4:5], v[166:167], v[46:47] op_sel_hi:[0,1,1]
	v_cvt_scalef32_pk_f32_fp4 v[170:171], v39, 1.0 op_sel:[1,0,0]
	v_pk_fma_f32 v[44:45], s[4:5], v[168:169], v[44:45] op_sel_hi:[0,1,1]
	v_cvt_scalef32_pk_f32_fp4 v[172:173], v39, 1.0 op_sel:[0,1,0]
	v_pk_fma_f32 v[42:43], s[4:5], v[170:171], v[42:43] op_sel_hi:[0,1,1]
	v_cvt_scalef32_pk_f32_fp4 v[174:175], v39, 1.0 op_sel:[1,1,0]
	v_pk_fma_f32 v[54:55], s[4:5], v[172:173], v[54:55] op_sel_hi:[0,1,1]
	v_pk_fma_f32 v[56:57], s[4:5], v[174:175], v[56:57] op_sel_hi:[0,1,1]
	global_load_dwordx2 v[38:39], v145, s[52:53]
	s_waitcnt vmcnt(11)
	v_readlane_b32 s4, v12, 17
	v_cvt_scalef32_pk_f32_fp4 v[160:161], v36, 1.0
	v_cvt_scalef32_pk_f32_fp4 v[162:163], v36, 1.0 op_sel:[1,0,0]
	v_pk_fma_f32 v[52:53], s[4:5], v[160:161], v[52:53] op_sel_hi:[0,1,1]
	v_cvt_scalef32_pk_f32_fp4 v[164:165], v36, 1.0 op_sel:[0,1,0]
	v_pk_fma_f32 v[50:51], s[4:5], v[162:163], v[50:51] op_sel_hi:[0,1,1]
	v_cvt_scalef32_pk_f32_fp4 v[166:167], v36, 1.0 op_sel:[1,1,0]
	v_pk_fma_f32 v[48:49], s[4:5], v[164:165], v[48:49] op_sel_hi:[0,1,1]
	v_cvt_scalef32_pk_f32_fp4 v[168:169], v37, 1.0
	v_pk_fma_f32 v[46:47], s[4:5], v[166:167], v[46:47] op_sel_hi:[0,1,1]
	v_cvt_scalef32_pk_f32_fp4 v[170:171], v37, 1.0 op_sel:[1,0,0]
	v_pk_fma_f32 v[44:45], s[4:5], v[168:169], v[44:45] op_sel_hi:[0,1,1]
	v_cvt_scalef32_pk_f32_fp4 v[172:173], v37, 1.0 op_sel:[0,1,0]
	v_pk_fma_f32 v[42:43], s[4:5], v[170:171], v[42:43] op_sel_hi:[0,1,1]
	v_cvt_scalef32_pk_f32_fp4 v[174:175], v37, 1.0 op_sel:[1,1,0]
	v_pk_fma_f32 v[54:55], s[4:5], v[172:173], v[54:55] op_sel_hi:[0,1,1]
	v_pk_fma_f32 v[56:57], s[4:5], v[174:175], v[56:57] op_sel_hi:[0,1,1]
	global_load_dwordx2 v[36:37], v146, s[52:53]
	s_waitcnt vmcnt(11)
	v_readlane_b32 s4, v12, 19
	v_cvt_scalef32_pk_f32_fp4 v[160:161], v34, 1.0
	v_cvt_scalef32_pk_f32_fp4 v[162:163], v34, 1.0 op_sel:[1,0,0]
	v_pk_fma_f32 v[52:53], s[4:5], v[160:161], v[52:53] op_sel_hi:[0,1,1]
	v_cvt_scalef32_pk_f32_fp4 v[164:165], v34, 1.0 op_sel:[0,1,0]
	v_pk_fma_f32 v[50:51], s[4:5], v[162:163], v[50:51] op_sel_hi:[0,1,1]
	v_cvt_scalef32_pk_f32_fp4 v[166:167], v34, 1.0 op_sel:[1,1,0]
	v_pk_fma_f32 v[48:49], s[4:5], v[164:165], v[48:49] op_sel_hi:[0,1,1]
	v_cvt_scalef32_pk_f32_fp4 v[168:169], v35, 1.0
	v_pk_fma_f32 v[46:47], s[4:5], v[166:167], v[46:47] op_sel_hi:[0,1,1]
	v_cvt_scalef32_pk_f32_fp4 v[170:171], v35, 1.0 op_sel:[1,0,0]
	v_pk_fma_f32 v[44:45], s[4:5], v[168:169], v[44:45] op_sel_hi:[0,1,1]
	v_cvt_scalef32_pk_f32_fp4 v[172:173], v35, 1.0 op_sel:[0,1,0]
	v_pk_fma_f32 v[42:43], s[4:5], v[170:171], v[42:43] op_sel_hi:[0,1,1]
	v_cvt_scalef32_pk_f32_fp4 v[174:175], v35, 1.0 op_sel:[1,1,0]
	v_pk_fma_f32 v[54:55], s[4:5], v[172:173], v[54:55] op_sel_hi:[0,1,1]
	v_pk_fma_f32 v[56:57], s[4:5], v[174:175], v[56:57] op_sel_hi:[0,1,1]
	global_load_dwordx2 v[34:35], v147, s[52:53]
	s_add_i32 s5, s5, 16
	s_cmpk_eq_i32 s5, 0x1f0
	s_cbranch_scc0 .LBB0_1075
; __device__ __forceinline__ float p3_weight(const int (&pt)[4], int lane, float sh, int hs8, const P3Sc& sc) {
;     int m2[2], m1;
;     const bool c0 = lane & 1;
; #pragma unroll
;     for (int j = 0; j < 2; j++) { const int keep = c0 ? pt[j + 2] : pt[j], send = c0 ? pt[j] : pt[j + 2]; m2[j] = keep + dpp_i<0xB1>(send); }
;     const bool c1 = lane & 2;
;     { const int keep = c1 ? m2[1] : m2[0], send = c1 ? m2[0] : m2[1]; m1 = keep + dpp_i<0x4E>(send); }
;     m1 += dpp_i<0x124>(m1);
;     m1 += dpp_i<0x128>(m1);
;     m1 = xrow_sum_i(m1);
;     const float aval = (float)(m1 - hs8) * sc.su;
;     return sc.gm * gelu_erf(aval);
; }
; __device__ __forceinline__ void p3_axpy(const u32x2 (&vr)[4], float ws, f32x2 (&acc)[8]) {
; #pragma unroll
;     for (int u = 0; u < 4; u++) {
;         const int la = ((u >> 1) & 1) | ((u & 1) << 1);
;         const float wu = __builtin_bit_cast(float, __builtin_amdgcn_readlane(__builtin_bit_cast(int, ws), la));
;         const f32x2 w2 = {wu, wu};
;         const unsigned vw[2] = {vr[u].x, vr[u].y};
; #pragma unroll
;         for (int i = 0; i < 2; i++) {
;             acc[i * 4 + 0] = __builtin_elementwise_fma(w2, __builtin_amdgcn_cvt_scalef32_pk_f32_fp4(vw[i], 1.0f, 0), acc[i * 4 + 0]);
;             acc[i * 4 + 1] = __builtin_elementwise_fma(w2, __builtin_amdgcn_cvt_scalef32_pk_f32_fp4(vw[i], 1.0f, 1), acc[i * 4 + 1]);
;             acc[i * 4 + 2] = __builtin_elementwise_fma(w2, __builtin_amdgcn_cvt_scalef32_pk_f32_fp4(vw[i], 1.0f, 2), acc[i * 4 + 2]);
;             acc[i * 4 + 3] = __builtin_elementwise_fma(w2, __builtin_amdgcn_cvt_scalef32_pk_f32_fp4(vw[i], 1.0f, 3), acc[i * 4 + 3]);
;         }
;     }
; __device__ __forceinline__ void p3_finish(const Params& p, float* dstp, int tok, int lane, const f32x2 (&acc)[8], float* tr) {
;     const float* mod = (const float*)(p.ws + OFF_MOD);
;     const int b = tok >> 11;
;     float own[16];
; #pragma unroll
;     for (int i = 0; i < 16; i++) own[i] = acc[i >> 1][i & 1];
;     const int d0 = lane * 16;
;     float x2[16];
;     float ss = 0.f;
;     const bf16_t* x1b = (const bf16_t*)(p.ws + OFF_X1B) + (size_t)tok * DM + d0;
;     const u32x4 xa = *(const u32x4*)x1b, xb = *(const u32x4*)(x1b + 8);
;     const unsigned xw[8] = {xa.x, xa.y, xa.z, xa.w, xb.x, xb.y, xb.z, xb.w};
; #pragma unroll
;     for (int i = 0; i < 4; i++) {
;         const int d = d0 + i * 4;
	v_add_u32_e32 v135, 0x1e0, v120
	ds_read2st64_b32 v[104:105], v135 offset1:6
	ds_read2st64_b32 v[102:103], v135 offset0:10 offset1:16
	s_waitcnt vmcnt(0) lgkmcnt(0)
	ds_read_b64 v[80:81], v149
	ds_read_b64 v[74:75], v149 offset:512
	ds_read_b64 v[84:85], v149 offset:1024
	ds_read_b64 v[82:83], v149 offset:1536
	ds_read_b64 v[66:67], v149 offset:2048
	ds_read_b64 v[60:61], v149 offset:2560
	ds_read_b64 v[68:69], v149 offset:3072
	ds_read_b64 v[64:65], v149 offset:3584
	s_waitcnt lgkmcnt(0)
	v_mov_b32_e32 v12, v13
	v_mov_b32_e32 v27, v13
	s_waitcnt vmcnt(8)
	v_dot8c_i32_i4_e32 v12, v82, v4
	v_dot8c_i32_i4_e32 v27, v82, v5
	v_dot8c_i32_i4_e32 v12, v83, v6
	v_dot8c_i32_i4_e32 v27, v83, v7
	v_mov_b32_e32 v76, v13
	v_dot8c_i32_i4_e32 v76, v84, v5
	v_dot8c_i32_i4_e32 v76, v85, v7
	v_lshl_add_u32 v12, v12, 4, v27
	v_mov_b32_e32 v27, v13
	v_dot8c_i32_i4_e32 v27, v84, v4
	v_dot8c_i32_i4_e32 v27, v85, v6
	v_mov_b32_e32 v77, v13
	v_dot8c_i32_i4_e32 v77, v74, v5
	v_dot8c_i32_i4_e32 v77, v75, v7
	v_lshl_add_u32 v27, v27, 4, v76
	v_mov_b32_e32 v76, v13
	v_dot8c_i32_i4_e32 v76, v74, v4
	v_dot8c_i32_i4_e32 v76, v75, v6
	v_mov_b32_e32 v75, v13
	v_dot8c_i32_i4_e32 v75, v80, v4
	v_mov_b32_e32 v4, v13
	v_dot8c_i32_i4_e32 v4, v80, v5
	v_dot8c_i32_i4_e32 v75, v81, v6
	v_dot8c_i32_i4_e32 v4, v81, v7
	v_lshl_add_u32 v74, v76, 4, v77
	v_cndmask_b32_e64 v6, v74, v12, s[0:1]
	v_cvt_scalef32_pk_f32_fp4 v[76:77], v72, 1.0 op_sel:[1,1,0]
	v_lshl_add_u32 v4, v75, 4, v4
	v_cndmask_b32_e64 v5, v27, v4, s[0:1]
	v_cndmask_b32_e64 v4, v4, v27, s[0:1]
	v_cvt_scalef32_pk_f32_fp4 v[78:79], v73, 1.0
	v_cvt_scalef32_pk_f32_fp4 v[80:81], v73, 1.0 op_sel:[1,0,0]
	v_add_u32_dpp v4, v4, v5 quad_perm:[1,0,3,2] row_mask:0xf bank_mask:0xf bound_ctrl:1
	v_cndmask_b32_e64 v5, v12, v74, s[0:1]
	v_cvt_scalef32_pk_f32_fp4 v[74:75], v72, 1.0 op_sel:[0,1,0]
	v_cvt_scalef32_pk_f32_fp4 v[82:83], v73, 1.0 op_sel:[0,1,0]
	v_add_u32_dpp v5, v6, v5 quad_perm:[1,0,3,2] row_mask:0xf bank_mask:0xf bound_ctrl:1
	v_cndmask_b32_e64 v6, v5, v4, s[2:3]
	v_cndmask_b32_e64 v4, v4, v5, s[2:3]
	v_cvt_scalef32_pk_f32_fp4 v[84:85], v70, 1.0
	v_lshl_add_u64 v[28:29], v[22:23], 0, v[28:29]
	v_add_u32_dpp v4, v4, v6 quad_perm:[2,3,0,1] row_mask:0xf bank_mask:0xf bound_ctrl:1
	v_mov_b32_e32 v27, v13
	v_cvt_scalef32_pk_f32_fp4 v[108:109], v62, 1.0 op_sel:[0,1,0]
	v_add_u32_dpp v4, v4, v4 row_ror:4 row_mask:0xf bank_mask:0xf bound_ctrl:1
	s_nop 1
	v_add_u32_dpp v4, v4, v4 row_ror:8 row_mask:0xf bank_mask:0xf bound_ctrl:1
	v_mov_b32_e32 v5, v4
	s_nop 1
	v_permlane16_swap_b32_e32 v4, v5
	v_add_u32_e32 v4, v4, v5
	v_mov_b32_e32 v5, v4
	s_nop 1
	v_permlane32_swap_b32_e32 v4, v5
	v_add_u32_e32 v4, v5, v4
	v_cvt_f32_i32_e32 v4, v4
	v_mul_f32_e32 v4, v105, v4
	v_fma_f32 v5, |v4|, s39, 1.0
	v_rcp_f32_e32 v5, v5
	v_mul_f32_e32 v7, v4, v4
	v_mul_f32_e32 v7, 0xbf38aa3b, v7
	v_exp_f32_e32 v7, v7
	v_fmamk_f32 v6, v5, 0x3f07dc22, v129
	v_fmaak_f32 v6, v5, v6, 0x3f35f0e3
	v_fmaak_f32 v6, v5, v6, 0xbe11a98e
	v_fmaak_f32 v6, v5, v6, 0x3e027906
	v_mul_f32_e32 v5, v5, v6
	v_mul_f32_e32 v5, v7, v5
	v_mul_f32_e32 v6, v4, v5
	v_fma_f32 v5, -v4, v5, v4
	v_cmp_gt_f32_e32 vcc, 0, v4
	s_nop 1
	v_cndmask_b32_e32 v4, v5, v6, vcc
	v_mul_f32_e32 v12, v104, v4
	v_cvt_scalef32_pk_f32_fp4 v[4:5], v72, 1.0
	v_readlane_b32 s4, v12, 0
	v_cvt_scalef32_pk_f32_fp4 v[6:7], v72, 1.0 op_sel:[1,0,0]
	v_cvt_scalef32_pk_f32_fp4 v[72:73], v73, 1.0 op_sel:[1,1,0]
	v_pk_fma_f32 v[4:5], s[4:5], v[4:5], v[100:101] op_sel_hi:[0,1,1]
	v_pk_fma_f32 v[6:7], s[4:5], v[6:7], v[98:99] op_sel_hi:[0,1,1]
	v_pk_fma_f32 v[74:75], s[4:5], v[74:75], v[96:97] op_sel_hi:[0,1,1]
	v_pk_fma_f32 v[76:77], s[4:5], v[76:77], v[94:95] op_sel_hi:[0,1,1]
	v_pk_fma_f32 v[78:79], s[4:5], v[78:79], v[92:93] op_sel_hi:[0,1,1]
	v_pk_fma_f32 v[80:81], s[4:5], v[80:81], v[90:91] op_sel_hi:[0,1,1]
	v_pk_fma_f32 v[82:83], s[4:5], v[82:83], v[88:89] op_sel_hi:[0,1,1]
	v_pk_fma_f32 v[72:73], s[4:5], v[72:73], v[86:87] op_sel_hi:[0,1,1]
	v_readlane_b32 s4, v12, 2
	s_nop 1
	v_pk_fma_f32 v[4:5], s[4:5], v[84:85], v[4:5] op_sel_hi:[0,1,1]
	v_cvt_scalef32_pk_f32_fp4 v[84:85], v70, 1.0 op_sel:[1,0,0]
	v_pk_fma_f32 v[84:85], s[4:5], v[84:85], v[6:7] op_sel_hi:[0,1,1]
	v_cvt_scalef32_pk_f32_fp4 v[6:7], v70, 1.0 op_sel:[0,1,0]
	v_pk_fma_f32 v[90:91], s[4:5], v[6:7], v[74:75] op_sel_hi:[0,1,1]
	v_cvt_scalef32_pk_f32_fp4 v[6:7], v70, 1.0 op_sel:[1,1,0]
	v_pk_fma_f32 v[92:93], s[4:5], v[6:7], v[76:77] op_sel_hi:[0,1,1]
	v_cvt_scalef32_pk_f32_fp4 v[6:7], v71, 1.0
	v_pk_fma_f32 v[94:95], s[4:5], v[6:7], v[78:79] op_sel_hi:[0,1,1]
	v_cvt_scalef32_pk_f32_fp4 v[6:7], v71, 1.0 op_sel:[1,0,0]
	v_pk_fma_f32 v[96:97], s[4:5], v[6:7], v[80:81] op_sel_hi:[0,1,1]
	v_cvt_scalef32_pk_f32_fp4 v[6:7], v71, 1.0 op_sel:[0,1,0]
	v_pk_fma_f32 v[98:99], s[4:5], v[6:7], v[82:83] op_sel_hi:[0,1,1]
	v_cvt_scalef32_pk_f32_fp4 v[6:7], v71, 1.0 op_sel:[1,1,0]
	v_pk_fma_f32 v[100:101], s[4:5], v[6:7], v[72:73] op_sel_hi:[0,1,1]
	v_ashrrev_i32_e32 v6, 11, v8
	v_mul_i32_i24_e32 v6, 0x1800, v6
	v_ashrrev_i32_e32 v7, 31, v6
	v_lshl_add_u64 v[6:7], v[6:7], 2, s[22:23]
	v_readlane_b32 s4, v12, 1
	global_load_dwordx4 v[70:73], v[28:29], off offset:16
	global_load_dwordx4 v[74:77], v[28:29], off
	v_lshl_add_u64 v[28:29], v[6:7], 0, v[26:27]
	v_cvt_scalef32_pk_f32_fp4 v[82:83], v62, 1.0
	v_add_co_u32_e32 v6, vcc, s40, v28
	v_pk_fma_f32 v[104:105], s[4:5], v[82:83], v[4:5] op_sel_hi:[0,1,1]
	v_cvt_scalef32_pk_f32_fp4 v[4:5], v62, 1.0 op_sel:[1,0,0]
	v_addc_co_u32_e32 v7, vcc, 0, v29, vcc
	v_pk_fma_f32 v[106:107], s[4:5], v[4:5], v[84:85] op_sel_hi:[0,1,1]
	v_lshl_add_u64 v[4:5], v[28:29], 0, s[30:31]
	v_pk_fma_f32 v[28:29], s[4:5], v[108:109], v[90:91] op_sel_hi:[0,1,1]
	v_cvt_scalef32_pk_f32_fp4 v[90:91], v62, 1.0 op_sel:[1,1,0]
	v_pk_fma_f32 v[108:109], s[4:5], v[90:91], v[92:93] op_sel_hi:[0,1,1]
	v_cvt_scalef32_pk_f32_fp4 v[90:91], v63, 1.0
	global_load_dwordx4 v[78:81], v[6:7], off
	v_pk_fma_f32 v[94:95], s[4:5], v[90:91], v[94:95] op_sel_hi:[0,1,1]
	v_cvt_scalef32_pk_f32_fp4 v[90:91], v63, 1.0 op_sel:[1,0,0]
	global_load_dwordx4 v[82:85], v[4:5], off offset:32
	global_load_dwordx4 v[86:89], v[4:5], off offset:16
	v_pk_fma_f32 v[96:97], s[4:5], v[90:91], v[96:97] op_sel_hi:[0,1,1]
	v_cvt_scalef32_pk_f32_fp4 v[90:91], v63, 1.0 op_sel:[0,1,0]
	v_cvt_scalef32_pk_f32_fp4 v[62:63], v63, 1.0 op_sel:[1,1,0]
	v_pk_fma_f32 v[98:99], s[4:5], v[90:91], v[98:99] op_sel_hi:[0,1,1]
	v_pk_fma_f32 v[62:63], s[4:5], v[62:63], v[100:101] op_sel_hi:[0,1,1]
	v_readlane_b32 s4, v12, 3
	s_waitcnt vmcnt(11)
; __device__ __forceinline__ void p3_dots(const u32x2 (&ur)[4], const unsigned* rec, int lane, int (&pt)[4]) {
;     const u32x4 qh = *(const u32x4*)(rec + 256 + lane * 4);
; #pragma unroll
;     for (int u = 0; u < 4; u++) {
;         const int w0 = (int)ur[u].x, w1 = (int)ur[u].y;
;         int dh = __builtin_amdgcn_sdot8(w0, (int)qh.x, 0, false);
;         dh = __builtin_amdgcn_sdot8(w1, (int)qh.z, dh, false);
;         int dl = __builtin_amdgcn_sdot8(w0, (int)qh.y, 0, false);
;         dl = __builtin_amdgcn_sdot8(w1, (int)qh.w, dl, false);
;         pt[u] = (dh << 4) + dl;
;     }
; }
; template <int CTRL> __device__ __forceinline__ int dpp_i(int v) { return __builtin_amdgcn_mov_dpp(v, CTRL, 0xF, 0xF, true); }
; __device__ __forceinline__ int xrow_sum_i(int v) {
;     const auto a = __builtin_amdgcn_permlane16_swap((unsigned)v, (unsigned)v, false, false);
;     v = (int)a[0] + (int)a[1];
;     const auto b = __builtin_amdgcn_permlane32_swap((unsigned)v, (unsigned)v, false, false);
;     return (int)b[0] + (int)b[1];
; }
; __device__ __forceinline__ float p3_weight(const int (&pt)[4], int lane, float sh, int hs8, const P3Sc& sc) {
;     int m2[2], m1;
;     const bool c0 = lane & 1;
; #pragma unroll
;     for (int j = 0; j < 2; j++) { const int keep = c0 ? pt[j + 2] : pt[j], send = c0 ? pt[j] : pt[j + 2]; m2[j] = keep + dpp_i<0xB1>(send); }
;     const bool c1 = lane & 2;
;     { const int keep = c1 ? m2[1] : m2[0], send = c1 ? m2[0] : m2[1]; m1 = keep + dpp_i<0x4E>(send); }
;     m1 += dpp_i<0x124>(m1);
;     m1 += dpp_i<0x128>(m1);
;     m1 = xrow_sum_i(m1);
;     const float aval = (float)(m1 - hs8) * sc.su;
;     return sc.gm * gelu_erf(aval);
; }
; __device__ __forceinline__ void p3_finish(const Params& p, float* dstp, int tok, int lane, const f32x2 (&acc)[8], float* tr) {
;     ...
;     const bf16_t* x1b = (const bf16_t*)(p.ws + OFF_X1B) + (size_t)tok * DM + d0;
;     const u32x4 xa = *(const u32x4*)x1b, xb = *(const u32x4*)(x1b + 8);
;     const unsigned xw[8] = {xa.x, xa.y, xa.z, xa.w, xb.x, xb.y, xb.z, xb.w};
; #pragma unroll
;     for (int i = 0; i < 4; i++) {
;         const int d = d0 + i * 4;
;         const f32x4 xv = {bf_lo(xw[2 * i]), bf_hi(xw[2 * i]), bf_lo(xw[2 * i + 1]), bf_hi(xw[2 * i + 1])};
;         const f32x4 gt = *(const f32x4*)(mod + b * 6144 + 5 * 1024 + d);
; #pragma unroll
	v_cvt_scalef32_pk_f32_fp4 v[90:91], v58, 1.0
	v_mov_b32_e32 v12, v13
	v_pk_fma_f32 v[100:101], s[4:5], v[90:91], v[104:105] op_sel_hi:[0,1,1]
	global_load_dwordx4 v[90:93], v[4:5], off offset:48
	v_cvt_scalef32_pk_f32_fp4 v[104:105], v58, 1.0 op_sel:[1,0,0]
	v_pk_fma_f32 v[104:105], s[4:5], v[104:105], v[106:107] op_sel_hi:[0,1,1]
	v_cvt_scalef32_pk_f32_fp4 v[106:107], v58, 1.0 op_sel:[0,1,0]
	v_pk_fma_f32 v[28:29], s[4:5], v[106:107], v[28:29] op_sel_hi:[0,1,1]
	v_cvt_scalef32_pk_f32_fp4 v[106:107], v58, 1.0 op_sel:[1,1,0]
	v_pk_fma_f32 v[106:107], s[4:5], v[106:107], v[108:109] op_sel_hi:[0,1,1]
	v_cvt_scalef32_pk_f32_fp4 v[108:109], v59, 1.0
	v_pk_fma_f32 v[94:95], s[4:5], v[108:109], v[94:95] op_sel_hi:[0,1,1]
	v_cvt_scalef32_pk_f32_fp4 v[108:109], v59, 1.0 op_sel:[1,0,0]
	s_waitcnt vmcnt(9)
	v_dot8c_i32_i4_e32 v12, v64, v0
	v_dot8c_i32_i4_e32 v27, v64, v1
	v_pk_fma_f32 v[96:97], s[4:5], v[108:109], v[96:97] op_sel_hi:[0,1,1]
	v_cvt_scalef32_pk_f32_fp4 v[108:109], v59, 1.0 op_sel:[0,1,0]
	v_cvt_scalef32_pk_f32_fp4 v[58:59], v59, 1.0 op_sel:[1,1,0]
	v_dot8c_i32_i4_e32 v12, v65, v2
	v_dot8c_i32_i4_e32 v27, v65, v3
	v_pk_fma_f32 v[98:99], s[4:5], v[108:109], v[98:99] op_sel_hi:[0,1,1]
	v_pk_fma_f32 v[108:109], s[4:5], v[58:59], v[62:63] op_sel_hi:[0,1,1]
	v_mov_b32_e32 v58, v13
	v_lshl_add_u32 v12, v12, 4, v27
	v_mov_b32_e32 v27, v13
	v_dot8c_i32_i4_e32 v27, v68, v0
	v_dot8c_i32_i4_e32 v58, v68, v1
	v_dot8c_i32_i4_e32 v27, v69, v2
	v_dot8c_i32_i4_e32 v58, v69, v3
	v_mov_b32_e32 v59, v13
	s_waitcnt vmcnt(7)
	v_dot8c_i32_i4_e32 v59, v60, v1
	v_dot8c_i32_i4_e32 v59, v61, v3
	v_lshl_add_u32 v27, v27, 4, v58
	v_mov_b32_e32 v58, v13
	v_dot8c_i32_i4_e32 v58, v60, v0
	v_dot8c_i32_i4_e32 v58, v61, v2
	s_waitcnt vmcnt(4)
	v_lshlrev_b32_e32 v110, 16, v74
	s_nop 0
	v_lshl_add_u32 v58, v58, 4, v59
	v_mov_b32_e32 v59, v13
	v_dot8c_i32_i4_e32 v59, v66, v0
	v_mov_b32_e32 v0, v13
	v_dot8c_i32_i4_e32 v0, v66, v1
	v_dot8c_i32_i4_e32 v59, v67, v2
	v_dot8c_i32_i4_e32 v0, v67, v3
	v_cndmask_b32_e64 v2, v58, v12, s[0:1]
	v_and_b32_e32 v111, 0xffff0000, v74
	v_lshlrev_b32_e32 v74, 16, v75
	v_lshl_add_u32 v0, v59, 4, v0
	v_cndmask_b32_e64 v1, v27, v0, s[0:1]
	v_cndmask_b32_e64 v0, v0, v27, s[0:1]
	v_and_b32_e32 v75, 0xffff0000, v75
	s_waitcnt vmcnt(3)
	v_pk_fma_f32 v[74:75], v[104:105], v[80:81], v[74:75]
	v_add_u32_dpp v0, v0, v1 quad_perm:[1,0,3,2] row_mask:0xf bank_mask:0xf bound_ctrl:1
	v_cndmask_b32_e64 v1, v12, v58, s[0:1]
	v_lshlrev_b32_e32 v104, 16, v76
	v_and_b32_e32 v105, 0xffff0000, v76
	v_add_u32_dpp v1, v2, v1 quad_perm:[1,0,3,2] row_mask:0xf bank_mask:0xf bound_ctrl:1
	v_cndmask_b32_e64 v12, v1, v0, s[2:3]
	v_cndmask_b32_e64 v27, v0, v1, s[2:3]
	global_load_dwordx4 v[0:3], v[24:25], off offset:48
	global_load_dwordx4 v[58:61], v[24:25], off offset:32
	global_load_dwordx4 v[62:65], v[24:25], off offset:16
	global_load_dwordx4 v[66:69], v[24:25], off
	v_pk_fma_f32 v[78:79], v[100:101], v[78:79], v[110:111]
	s_waitcnt vmcnt(5)
	v_pk_fma_f32 v[28:29], v[28:29], v[86:87], v[104:105]
	v_lshlrev_b32_e32 v104, 16, v70
	v_and_b32_e32 v105, 0xffff0000, v70
	v_lshlrev_b32_e32 v70, 16, v71
	v_and_b32_e32 v71, 0xffff0000, v71
	v_pk_mul_f32 v[100:101], v[78:79], v[78:79]
	v_pk_fma_f32 v[70:71], v[96:97], v[84:85], v[70:71]
	v_lshlrev_b32_e32 v96, 16, v72
	v_and_b32_e32 v97, 0xffff0000, v72
	v_pk_mul_f32 v[80:81], v[74:75], v[74:75]
	s_waitcnt vmcnt(4)
	v_pk_fma_f32 v[90:91], v[98:99], v[90:91], v[96:97]
	v_add_f32_e32 v98, v100, v101
	v_add_f32_e32 v80, v80, v98
	v_pk_mul_f32 v[86:87], v[28:29], v[28:29]
	v_lshlrev_b32_e32 v76, 16, v77
	v_and_b32_e32 v77, 0xffff0000, v77
	v_add_f32_e32 v80, v81, v80
	v_pk_fma_f32 v[76:77], v[106:107], v[88:89], v[76:77]
	v_add_f32_e32 v80, v86, v80
	v_pk_mul_f32 v[88:89], v[76:77], v[76:77]
	v_add_f32_e32 v80, v87, v80
	v_pk_fma_f32 v[82:83], v[94:95], v[82:83], v[104:105]
	v_add_f32_e32 v80, v88, v80
	v_pk_mul_f32 v[94:95], v[82:83], v[82:83]
	v_add_f32_e32 v80, v89, v80
	v_add_f32_e32 v80, v94, v80
	v_pk_mul_f32 v[84:85], v[70:71], v[70:71]
	v_add_f32_e32 v80, v95, v80
	v_add_f32_e32 v80, v84, v80
	v_pk_mul_f32 v[96:97], v[90:91], v[90:91]
	v_lshlrev_b32_e32 v72, 16, v73
	v_and_b32_e32 v73, 0xffff0000, v73
	v_add_f32_e32 v80, v85, v80
	v_pk_fma_f32 v[72:73], v[108:109], v[92:93], v[72:73]
	v_add_f32_e32 v80, v96, v80
	v_pk_mul_f32 v[92:93], v[72:73], v[72:73]
	v_add_f32_e32 v80, v97, v80
	v_add_f32_e32 v80, v92, v80
	v_add_f32_e32 v80, v93, v80
	ds_bpermute_b32 v81, v112, v80
	v_add_u32_dpp v12, v27, v12 quad_perm:[2,3,0,1] row_mask:0xf bank_mask:0xf bound_ctrl:1
	s_waitcnt lgkmcnt(0)
	v_add_f32_e32 v80, v80, v81
	ds_bpermute_b32 v81, v113, v80
	v_add_u32_dpp v12, v12, v12 row_ror:4 row_mask:0xf bank_mask:0xf bound_ctrl:1
	s_waitcnt lgkmcnt(0)
	v_add_f32_e32 v80, v80, v81
	v_add_u32_dpp v12, v12, v12 row_ror:8 row_mask:0xf bank_mask:0xf bound_ctrl:1
	v_mov_b32_e32 v27, v12
	ds_bpermute_b32 v81, v114, v80
	s_nop 0
	v_permlane16_swap_b32_e32 v12, v27
	v_add_u32_e32 v12, v12, v27
	v_mov_b32_e32 v27, v12
	s_nop 1
	v_permlane32_swap_b32_e32 v12, v27
	v_add_u32_e32 v12, v27, v12
	s_waitcnt lgkmcnt(0)
	v_add_f32_e32 v27, v80, v81
	ds_bpermute_b32 v80, v115, v27
	v_cvt_f32_i32_e32 v12, v12
	s_waitcnt lgkmcnt(0)
	v_add_f32_e32 v27, v27, v80
	ds_bpermute_b32 v80, v116, v27
	v_mul_f32_e32 v81, v103, v12
	v_fma_f32 v12, |v81|, s39, 1.0
	v_rcp_f32_e32 v12, v12
	s_waitcnt lgkmcnt(0)
	v_add_f32_e32 v27, v27, v80
	ds_bpermute_b32 v80, v117, v27
	v_fmamk_f32 v84, v12, 0x3f07dc22, v129
	v_fmaak_f32 v84, v12, v84, 0x3f35f0e3
	v_fmaak_f32 v84, v12, v84, 0xbe11a98e
	v_fmaak_f32 v84, v12, v84, 0x3e027906
	s_waitcnt lgkmcnt(0)
; __device__ __forceinline__ void p3_axpy(const u32x2 (&vr)[4], float ws, f32x2 (&acc)[8]) {
; #pragma unroll
;     for (int u = 0; u < 4; u++) {
;         const int la = ((u >> 1) & 1) | ((u & 1) << 1);
;         const float wu = __builtin_bit_cast(float, __builtin_amdgcn_readlane(__builtin_bit_cast(int, ws), la));
;         const f32x2 w2 = {wu, wu};
;         const unsigned vw[2] = {vr[u].x, vr[u].y};
; #pragma unroll
;         for (int i = 0; i < 2; i++) {
;             acc[i * 4 + 0] = __builtin_elementwise_fma(w2, __builtin_amdgcn_cvt_scalef32_pk_f32_fp4(vw[i], 1.0f, 0), acc[i * 4 + 0]);
;             acc[i * 4 + 1] = __builtin_elementwise_fma(w2, __builtin_amdgcn_cvt_scalef32_pk_f32_fp4(vw[i], 1.0f, 1), acc[i * 4 + 1]);
;             acc[i * 4 + 2] = __builtin_elementwise_fma(w2, __builtin_amdgcn_cvt_scalef32_pk_f32_fp4(vw[i], 1.0f, 2), acc[i * 4 + 2]);
;             acc[i * 4 + 3] = __builtin_elementwise_fma(w2, __builtin_amdgcn_cvt_scalef32_pk_f32_fp4(vw[i], 1.0f, 3), acc[i * 4 + 3]);
;         }
;     }
; }
; __device__ __forceinline__ void p3_finish(const Params& p, float* dstp, int tok, int lane, const f32x2 (&acc)[8], float* tr) {
;     ...
;     ss = wave_sum(ss);
;     const float rstd = rsqrtf(ss * (1.f / 1024.f) + 1e-6f);
; #pragma unroll
;     for (int i = 0; i < 4; i++) {
;         const int d = d0 + i * 4;
;         const f32x4 fg = *(const f32x4*)(p.final_g + d);
;         f32x4 o;
; #pragma unroll
;         for (int j = 0; j < 4; j++) o[j] = x2[i * 4 + j] * rstd * fg[j];
;         *(f32x4*)(tr + d) = o;
;     }
;     __builtin_amdgcn_fence(__ATOMIC_RELEASE, "wavefront");
;     __builtin_amdgcn_wave_barrier();
;     __builtin_amdgcn_fence(__ATOMIC_ACQUIRE, "wavefront");
; #pragma unroll
;     for (int j = 0; j < 4; j++) {
;         const f32x4 v = *(const f32x4*)(tr + j * 256 + lane * 4);
;         *(f32x4*)(dstp + (size_t)tok * DM + j * 256 + lane * 4) = v;
;     }
;     __builtin_amdgcn_wave_barrier();
	v_add_f32_e32 v27, v27, v80
	v_mul_f32_e32 v12, v12, v84
	v_mul_f32_e32 v84, v81, v81
	v_fmamk_f32 v27, v27, 0x3a800000, v130
	v_mul_f32_e32 v84, 0xbf38aa3b, v84
	v_mul_f32_e32 v80, 0x4b800000, v27
	v_cmp_gt_f32_e32 vcc, s38, v27
	v_exp_f32_e32 v84, v84
	s_nop 0
	v_cndmask_b32_e32 v27, v27, v80, vcc
	v_rsq_f32_e32 v27, v27
	v_mul_f32_e32 v12, v84, v12
	v_mul_f32_e32 v80, v81, v12
	v_fma_f32 v84, -v81, v12, v81
	v_mul_f32_e32 v12, 0x45800000, v27
	v_cndmask_b32_e32 v12, v27, v12, vcc
	v_pk_mul_f32 v[78:79], v[78:79], v[12:13] op_sel_hi:[1,0]
	v_pk_mul_f32 v[74:75], v[74:75], v[12:13] op_sel_hi:[1,0]
	s_waitcnt vmcnt(0)
	v_pk_mul_f32 v[66:67], v[66:67], v[78:79]
	v_pk_mul_f32 v[68:69], v[68:69], v[74:75]
	ds_write_b128 v118, v[66:69]
	v_pk_mul_f32 v[28:29], v[28:29], v[12:13] op_sel_hi:[1,0]
	v_pk_mul_f32 v[66:67], v[76:77], v[12:13] op_sel_hi:[1,0]
	v_pk_mul_f32 v[62:63], v[62:63], v[28:29]
	v_pk_mul_f32 v[64:65], v[64:65], v[66:67]
	ds_write_b128 v118, v[62:65] offset:16
	v_pk_mul_f32 v[28:29], v[82:83], v[12:13] op_sel_hi:[1,0]
	v_pk_mul_f32 v[62:63], v[70:71], v[12:13] op_sel_hi:[1,0]
	v_pk_mul_f32 v[58:59], v[58:59], v[28:29]
	v_pk_mul_f32 v[60:61], v[60:61], v[62:63]
	ds_write_b128 v118, v[58:61] offset:32
	v_pk_mul_f32 v[28:29], v[90:91], v[12:13] op_sel_hi:[1,0]
	v_pk_mul_f32 v[58:59], v[72:73], v[12:13] op_sel_hi:[1,0]
	v_pk_mul_f32 v[0:1], v[0:1], v[28:29]
	v_pk_mul_f32 v[2:3], v[2:3], v[58:59]
	ds_write_b128 v118, v[0:3] offset:48
	ds_read_b128 v[0:3], v128
	ds_read_b128 v[58:61], v128 offset:1024
	ds_read_b128 v[62:65], v128 offset:2048
	ds_read_b128 v[66:69], v128 offset:3072
	v_lshlrev_b64 v[28:29], 12, v[8:9]
	v_lshl_add_u64 v[28:29], v[18:19], 0, v[28:29]
	s_waitcnt lgkmcnt(3)
	global_store_dwordx4 v[28:29], v[0:3], off
	s_waitcnt lgkmcnt(2)
	global_store_dwordx4 v[28:29], v[58:61], off offset:1024
	s_waitcnt lgkmcnt(1)
	global_store_dwordx4 v[28:29], v[62:65], off offset:2048
	s_waitcnt lgkmcnt(0)
	global_store_dwordx4 v[28:29], v[66:69], off offset:3072
	v_lshl_add_u64 v[28:29], v[22:23], 0, v[32:33]
	global_load_dwordx4 v[0:3], v[28:29], off offset:16
	global_load_dwordx4 v[58:61], v[28:29], off
	global_load_dwordx4 v[62:65], v[6:7], off
	v_cmp_gt_f32_e32 vcc, 0, v81
	global_load_dwordx4 v[66:69], v[4:5], off offset:32
	global_load_dwordx4 v[70:73], v[4:5], off offset:16
	v_cndmask_b32_e32 v6, v84, v80, vcc
	v_mul_f32_e32 v9, v102, v6
	v_cvt_scalef32_pk_f32_fp4 v[6:7], v40, 1.0
	v_readlane_b32 s4, v9, 0
	v_add_u32_e32 v8, s36, v8
	s_waitcnt vmcnt(3)
	v_lshlrev_b32_e32 v78, 16, v58
	v_pk_fma_f32 v[28:29], s[4:5], v[6:7], v[52:53] op_sel_hi:[0,1,1]
	v_cvt_scalef32_pk_f32_fp4 v[6:7], v40, 1.0 op_sel:[1,0,0]
	v_pk_fma_f32 v[32:33], s[4:5], v[6:7], v[50:51] op_sel_hi:[0,1,1]
	v_cvt_scalef32_pk_f32_fp4 v[6:7], v40, 1.0 op_sel:[0,1,0]
	v_pk_fma_f32 v[48:49], s[4:5], v[6:7], v[48:49] op_sel_hi:[0,1,1]
	v_cvt_scalef32_pk_f32_fp4 v[6:7], v40, 1.0 op_sel:[1,1,0]
	v_pk_fma_f32 v[46:47], s[4:5], v[6:7], v[46:47] op_sel_hi:[0,1,1]
	v_cvt_scalef32_pk_f32_fp4 v[6:7], v41, 1.0
	v_pk_fma_f32 v[44:45], s[4:5], v[6:7], v[44:45] op_sel_hi:[0,1,1]
	v_cvt_scalef32_pk_f32_fp4 v[6:7], v41, 1.0 op_sel:[1,0,0]
	v_pk_fma_f32 v[42:43], s[4:5], v[6:7], v[42:43] op_sel_hi:[0,1,1]
	v_cvt_scalef32_pk_f32_fp4 v[6:7], v41, 1.0 op_sel:[0,1,0]
	v_pk_fma_f32 v[50:51], s[4:5], v[6:7], v[54:55] op_sel_hi:[0,1,1]
	v_cvt_scalef32_pk_f32_fp4 v[6:7], v41, 1.0 op_sel:[1,1,0]
	v_pk_fma_f32 v[40:41], s[4:5], v[6:7], v[56:57] op_sel_hi:[0,1,1]
	global_load_dwordx4 v[4:7], v[4:5], off offset:48
	v_readlane_b32 s4, v9, 2
	v_cvt_scalef32_pk_f32_fp4 v[52:53], v38, 1.0
	v_and_b32_e32 v79, 0xffff0000, v58
	v_pk_fma_f32 v[28:29], s[4:5], v[52:53], v[28:29] op_sel_hi:[0,1,1]
	v_cvt_scalef32_pk_f32_fp4 v[52:53], v38, 1.0 op_sel:[1,0,0]
	v_pk_fma_f32 v[32:33], s[4:5], v[52:53], v[32:33] op_sel_hi:[0,1,1]
	v_cvt_scalef32_pk_f32_fp4 v[52:53], v38, 1.0 op_sel:[0,1,0]
	v_pk_fma_f32 v[48:49], s[4:5], v[52:53], v[48:49] op_sel_hi:[0,1,1]
	v_cvt_scalef32_pk_f32_fp4 v[52:53], v38, 1.0 op_sel:[1,1,0]
	v_pk_fma_f32 v[46:47], s[4:5], v[52:53], v[46:47] op_sel_hi:[0,1,1]
	v_cvt_scalef32_pk_f32_fp4 v[52:53], v39, 1.0
	v_pk_fma_f32 v[44:45], s[4:5], v[52:53], v[44:45] op_sel_hi:[0,1,1]
	v_cvt_scalef32_pk_f32_fp4 v[52:53], v39, 1.0 op_sel:[1,0,0]
	v_pk_fma_f32 v[42:43], s[4:5], v[52:53], v[42:43] op_sel_hi:[0,1,1]
	v_cvt_scalef32_pk_f32_fp4 v[52:53], v39, 1.0 op_sel:[0,1,0]
	v_cvt_scalef32_pk_f32_fp4 v[38:39], v39, 1.0 op_sel:[1,1,0]
	v_pk_fma_f32 v[50:51], s[4:5], v[52:53], v[50:51] op_sel_hi:[0,1,1]
	v_pk_fma_f32 v[38:39], s[4:5], v[38:39], v[40:41] op_sel_hi:[0,1,1]
	v_readlane_b32 s4, v9, 1
	v_cvt_scalef32_pk_f32_fp4 v[40:41], v36, 1.0
	v_lshlrev_b32_e32 v58, 16, v59
	v_pk_fma_f32 v[28:29], s[4:5], v[40:41], v[28:29] op_sel_hi:[0,1,1]
	v_cvt_scalef32_pk_f32_fp4 v[40:41], v36, 1.0 op_sel:[1,0,0]
	v_pk_fma_f32 v[32:33], s[4:5], v[40:41], v[32:33] op_sel_hi:[0,1,1]
	v_cvt_scalef32_pk_f32_fp4 v[40:41], v36, 1.0 op_sel:[0,1,0]
	v_pk_fma_f32 v[40:41], s[4:5], v[40:41], v[48:49] op_sel_hi:[0,1,1]
	v_cvt_scalef32_pk_f32_fp4 v[48:49], v36, 1.0 op_sel:[1,1,0]
	v_pk_fma_f32 v[46:47], s[4:5], v[48:49], v[46:47] op_sel_hi:[0,1,1]
	v_cvt_scalef32_pk_f32_fp4 v[48:49], v37, 1.0
	v_pk_fma_f32 v[44:45], s[4:5], v[48:49], v[44:45] op_sel_hi:[0,1,1]
	v_cvt_scalef32_pk_f32_fp4 v[48:49], v37, 1.0 op_sel:[1,0,0]
	v_pk_fma_f32 v[42:43], s[4:5], v[48:49], v[42:43] op_sel_hi:[0,1,1]
	v_cvt_scalef32_pk_f32_fp4 v[48:49], v37, 1.0 op_sel:[0,1,0]
	v_cvt_scalef32_pk_f32_fp4 v[36:37], v37, 1.0 op_sel:[1,1,0]
	v_pk_fma_f32 v[48:49], s[4:5], v[48:49], v[50:51] op_sel_hi:[0,1,1]
	v_pk_fma_f32 v[36:37], s[4:5], v[36:37], v[38:39] op_sel_hi:[0,1,1]
	v_readlane_b32 s4, v9, 3
	v_cvt_scalef32_pk_f32_fp4 v[38:39], v34, 1.0
	v_and_b32_e32 v59, 0xffff0000, v59
	v_pk_fma_f32 v[28:29], s[4:5], v[38:39], v[28:29] op_sel_hi:[0,1,1]
	v_cvt_scalef32_pk_f32_fp4 v[38:39], v34, 1.0 op_sel:[1,0,0]
	v_pk_fma_f32 v[50:51], s[4:5], v[38:39], v[32:33] op_sel_hi:[0,1,1]
	v_cvt_scalef32_pk_f32_fp4 v[32:33], v34, 1.0 op_sel:[0,1,0]
	v_pk_fma_f32 v[52:53], s[4:5], v[32:33], v[40:41] op_sel_hi:[0,1,1]
	v_cvt_scalef32_pk_f32_fp4 v[32:33], v34, 1.0 op_sel:[1,1,0]
	v_pk_fma_f32 v[54:55], s[4:5], v[32:33], v[46:47] op_sel_hi:[0,1,1]
	v_cvt_scalef32_pk_f32_fp4 v[32:33], v35, 1.0
	v_pk_fma_f32 v[56:57], s[4:5], v[32:33], v[44:45] op_sel_hi:[0,1,1]
	v_cvt_scalef32_pk_f32_fp4 v[32:33], v35, 1.0 op_sel:[1,0,0]
	v_pk_fma_f32 v[74:75], s[4:5], v[32:33], v[42:43] op_sel_hi:[0,1,1]
	v_cvt_scalef32_pk_f32_fp4 v[32:33], v35, 1.0 op_sel:[0,1,0]
	v_pk_fma_f32 v[48:49], s[4:5], v[32:33], v[48:49] op_sel_hi:[0,1,1]
	v_cvt_scalef32_pk_f32_fp4 v[32:33], v35, 1.0 op_sel:[1,1,0]
	v_pk_fma_f32 v[76:77], s[4:5], v[32:33], v[36:37] op_sel_hi:[0,1,1]
	global_load_dwordx4 v[32:35], v[24:25], off offset:48
	global_load_dwordx4 v[36:39], v[24:25], off offset:32
	global_load_dwordx4 v[40:43], v[24:25], off offset:16
	global_load_dwordx4 v[44:47], v[24:25], off
	s_waitcnt vmcnt(7)
; __device__ __forceinline__ float bf_lo(unsigned u) { return __uint_as_float(u << 16); }
; __device__ __forceinline__ float bf_hi(unsigned u) { return __uint_as_float(u & 0xffff0000u); }
; __device__ __forceinline__ void p3_finish(const Params& p, float* dstp, int tok, int lane, const f32x2 (&acc)[8], float* tr) {
;     ...
;     for (int i = 0; i < 4; i++) {
;         const int d = d0 + i * 4;
;         const f32x4 xv = {bf_lo(xw[2 * i]), bf_hi(xw[2 * i]), bf_lo(xw[2 * i + 1]), bf_hi(xw[2 * i + 1])};
;         const f32x4 gt = *(const f32x4*)(mod + b * 6144 + 5 * 1024 + d);
; #pragma unroll
;         for (int j = 0; j < 4; j++) { const float v = xv[j] + gt[j] * own[i * 4 + j]; x2[i * 4 + j] = v; ss += v * v; }
;     }
;     ss = wave_sum(ss);
;     const float rstd = rsqrtf(ss * (1.f / 1024.f) + 1e-6f);
; #pragma unroll
;     for (int i = 0; i < 4; i++) {
;         const int d = d0 + i * 4;
;         const f32x4 fg = *(const f32x4*)(p.final_g + d);
;         f32x4 o;
; #pragma unroll
;         for (int j = 0; j < 4; j++) o[j] = x2[i * 4 + j] * rstd * fg[j];
;         *(f32x4*)(tr + d) = o;
;     }
;     __builtin_amdgcn_fence(__ATOMIC_RELEASE, "wavefront");
;     __builtin_amdgcn_wave_barrier();
;     __builtin_amdgcn_fence(__ATOMIC_ACQUIRE, "wavefront");
; #pragma unroll
;     for (int j = 0; j < 4; j++) {
;         const f32x4 v = *(const f32x4*)(tr + j * 256 + lane * 4);
;         *(f32x4*)(dstp + (size_t)tok * DM + j * 256 + lane * 4) = v;
;     }
;     __builtin_amdgcn_wave_barrier();
	v_pk_fma_f32 v[28:29], v[28:29], v[62:63], v[78:79]
	v_pk_fma_f32 v[50:51], v[50:51], v[64:65], v[58:59]
	v_pk_mul_f32 v[62:63], v[28:29], v[28:29]
	v_pk_mul_f32 v[58:59], v[50:51], v[50:51]
	v_lshlrev_b32_e32 v64, 16, v60
	v_and_b32_e32 v65, 0xffff0000, v60
	v_add_f32_e32 v9, v62, v63
	s_waitcnt vmcnt(5)
	v_pk_fma_f32 v[52:53], v[52:53], v[70:71], v[64:65]
	v_add_f32_e32 v9, v58, v9
	v_pk_mul_f32 v[64:65], v[52:53], v[52:53]
	v_lshlrev_b32_e32 v60, 16, v61
	v_and_b32_e32 v61, 0xffff0000, v61
	v_add_f32_e32 v9, v59, v9
	v_pk_fma_f32 v[54:55], v[54:55], v[72:73], v[60:61]
	v_add_f32_e32 v9, v64, v9
	v_pk_mul_f32 v[60:61], v[54:55], v[54:55]
	v_lshlrev_b32_e32 v70, 16, v0
	v_and_b32_e32 v71, 0xffff0000, v0
	v_add_f32_e32 v9, v65, v9
	v_pk_fma_f32 v[56:57], v[56:57], v[66:67], v[70:71]
	v_add_f32_e32 v9, v60, v9
	v_pk_mul_f32 v[66:67], v[56:57], v[56:57]
	v_lshlrev_b32_e32 v0, 16, v1
	v_and_b32_e32 v1, 0xffff0000, v1
	v_add_f32_e32 v9, v61, v9
	v_pk_fma_f32 v[68:69], v[74:75], v[68:69], v[0:1]
	v_add_f32_e32 v9, v66, v9
	v_pk_mul_f32 v[0:1], v[68:69], v[68:69]
	v_lshlrev_b32_e32 v70, 16, v2
	v_and_b32_e32 v71, 0xffff0000, v2
	v_add_f32_e32 v9, v67, v9
	s_waitcnt vmcnt(4)
	v_pk_fma_f32 v[4:5], v[48:49], v[4:5], v[70:71]
	v_add_f32_e32 v0, v0, v9
	v_pk_mul_f32 v[48:49], v[4:5], v[4:5]
	v_lshlrev_b32_e32 v2, 16, v3
	v_and_b32_e32 v3, 0xffff0000, v3
	v_add_f32_e32 v0, v1, v0
	v_pk_fma_f32 v[6:7], v[76:77], v[6:7], v[2:3]
	v_add_f32_e32 v0, v48, v0
	v_pk_mul_f32 v[2:3], v[6:7], v[6:7]
	v_add_f32_e32 v0, v49, v0
	v_add_f32_e32 v0, v2, v0
	v_add_f32_e32 v0, v3, v0
	ds_bpermute_b32 v1, v112, v0
	s_waitcnt lgkmcnt(0)
	v_add_f32_e32 v0, v0, v1
	ds_bpermute_b32 v1, v113, v0
	s_waitcnt lgkmcnt(0)
	v_add_f32_e32 v0, v0, v1
	ds_bpermute_b32 v1, v114, v0
	s_waitcnt lgkmcnt(0)
	v_add_f32_e32 v0, v0, v1
	ds_bpermute_b32 v1, v115, v0
	s_waitcnt lgkmcnt(0)
	v_add_f32_e32 v0, v0, v1
	ds_bpermute_b32 v1, v116, v0
	s_waitcnt lgkmcnt(0)
	v_add_f32_e32 v0, v0, v1
	ds_bpermute_b32 v1, v117, v0
	s_waitcnt lgkmcnt(0)
	v_add_f32_e32 v0, v0, v1
	v_fmamk_f32 v0, v0, 0x3a800000, v130
	v_mul_f32_e32 v1, 0x4b800000, v0
	v_cmp_gt_f32_e32 vcc, s38, v0
	s_nop 1
	v_cndmask_b32_e32 v0, v0, v1, vcc
	v_rsq_f32_e32 v0, v0
	s_nop 0
	v_mul_f32_e32 v1, 0x45800000, v0
	v_cndmask_b32_e32 v12, v0, v1, vcc
	v_pk_mul_f32 v[0:1], v[28:29], v[12:13] op_sel_hi:[1,0]
	v_pk_mul_f32 v[2:3], v[50:51], v[12:13] op_sel_hi:[1,0]
	s_waitcnt vmcnt(0)
	v_pk_mul_f32 v[0:1], v[44:45], v[0:1]
	v_pk_mul_f32 v[2:3], v[46:47], v[2:3]
	ds_write_b128 v118, v[0:3]
	v_pk_mul_f32 v[0:1], v[52:53], v[12:13] op_sel_hi:[1,0]
	v_pk_mul_f32 v[2:3], v[54:55], v[12:13] op_sel_hi:[1,0]
	v_pk_mul_f32 v[0:1], v[40:41], v[0:1]
	v_pk_mul_f32 v[2:3], v[42:43], v[2:3]
	ds_write_b128 v118, v[0:3] offset:16
	v_pk_mul_f32 v[0:1], v[56:57], v[12:13] op_sel_hi:[1,0]
	v_pk_mul_f32 v[2:3], v[68:69], v[12:13] op_sel_hi:[1,0]
	v_pk_mul_f32 v[0:1], v[36:37], v[0:1]
	v_pk_mul_f32 v[2:3], v[38:39], v[2:3]
	ds_write_b128 v118, v[0:3] offset:32
	v_pk_mul_f32 v[0:1], v[4:5], v[12:13] op_sel_hi:[1,0]
	v_pk_mul_f32 v[2:3], v[6:7], v[12:13] op_sel_hi:[1,0]
	v_pk_mul_f32 v[0:1], v[32:33], v[0:1]
	v_pk_mul_f32 v[2:3], v[34:35], v[2:3]
	ds_write_b128 v118, v[0:3] offset:48
	ds_read_b128 v[0:3], v128
	ds_read_b128 v[4:7], v128 offset:1024
	v_lshlrev_b64 v[32:33], 12, v[30:31]
	v_lshl_add_u64 v[32:33], v[18:19], 0, v[32:33]
	ds_read_b128 v[28:31], v128 offset:2048
	s_waitcnt lgkmcnt(2)
	global_store_dwordx4 v[32:33], v[0:3], off
	s_waitcnt lgkmcnt(1)
	global_store_dwordx4 v[32:33], v[4:7], off offset:1024
	ds_read_b128 v[0:3], v128 offset:3072
	v_cmp_lt_i32_e32 vcc, s41, v8
	s_or_b64 s[28:29], vcc, s[28:29]
	s_waitcnt lgkmcnt(1)
	global_store_dwordx4 v[32:33], v[28:31], off offset:2048
	s_waitcnt lgkmcnt(0)
	global_store_dwordx4 v[32:33], v[0:3], off offset:3072
	s_andn2_b64 exec, exec, s[28:29]
	s_cbranch_execnz .LBB0_1042
